# GEMM K-loops: loop-carried counter and pointer increments moved in front of the iteration's closing barrier (loop-edge rotation); compare + branch stay at the bottom
# speedup vs baseline: 1.0019x; 1.0019x over previous
.LBB0_223:
	s_add_u32 s26, s24, 0xfffc0080
	s_addc_u32 s27, s25, -1
	s_add_i32 s34, 0, 0x10000
	s_cmp_eq_u32 s31, 12
	s_cselect_b32 s29, s8, s27
	s_cselect_b32 s28, s12, s26
	v_add_u32_e32 v148, s34, v151
	s_cselect_b32 s27, s13, s30
	s_cselect_b32 s26, s18, s23
	s_add_i32 s63, 0, 0x14000
	ds_read_b128 v[144:147], v148
	ds_read_b128 v[154:157], v148 offset:1024
	ds_read_b128 v[158:161], v148 offset:2048
	ds_read_b128 v[162:165], v148 offset:3072
	v_add_u32_e32 v148, s63, v151
	ds_read_b128 v[166:169], v148
	ds_read_b128 v[170:173], v148 offset:1024
	ds_read_b128 v[188:191], v148 offset:2048
	ds_read_b128 v[192:195], v148 offset:3072
	v_lshl_add_u64 v[148:149], s[24:25], 0, v[140:141]
	s_add_i32 m0, s43, 0xc000
	ds_read_b128 v[212:215], v153
	ds_read_b128 v[216:219], v153 offset:1024
	ds_read_b128 v[220:223], v153 offset:2048
	ds_read_b128 v[224:227], v153 offset:3072
	ds_read_b128 v[228:231], v153 offset:4096
	ds_read_b128 v[232:235], v153 offset:5120
	ds_read_b128 v[236:239], v153 offset:6144
	ds_read_b128 v[240:243], v153 offset:7168
	global_load_lds_dwordx4 v[148:149], off
	v_lshl_add_u64 v[148:149], s[24:25], 0, v[142:143]
	s_add_i32 m0, s43, 0xe000
	s_nop 0
	global_load_lds_dwordx4 v[148:149], off
	s_waitcnt vmcnt(8)
	s_waitcnt lgkmcnt(0)
	s_barrier
	s_setprio 1
	s_waitcnt lgkmcnt(0)
	v_mfma_f32_16x16x32_bf16 v[126:129], v[144:147], v[212:215], v[126:129]
	v_mfma_f32_16x16x32_bf16 v[122:125], v[158:161], v[212:215], v[122:125]
	v_mfma_f32_16x16x32_bf16 v[118:121], v[144:147], v[220:223], v[118:121]
	v_mfma_f32_16x16x32_bf16 v[110:113], v[158:161], v[220:223], v[110:113]
	v_mfma_f32_16x16x32_bf16 v[102:105], v[144:147], v[228:231], v[102:105]
	v_mfma_f32_16x16x32_bf16 v[94:97], v[158:161], v[228:231], v[94:97]
	v_mfma_f32_16x16x32_bf16 v[86:89], v[144:147], v[236:239], v[86:89]
	v_mfma_f32_16x16x32_bf16 v[78:81], v[158:161], v[236:239], v[78:81]
	v_mfma_f32_16x16x32_bf16 v[126:129], v[154:157], v[216:219], v[126:129]
	v_mfma_f32_16x16x32_bf16 v[122:125], v[162:165], v[216:219], v[122:125]
	v_mfma_f32_16x16x32_bf16 v[118:121], v[154:157], v[224:227], v[118:121]
	v_mfma_f32_16x16x32_bf16 v[110:113], v[162:165], v[224:227], v[110:113]
	v_mfma_f32_16x16x32_bf16 v[102:105], v[154:157], v[232:235], v[102:105]
	v_mfma_f32_16x16x32_bf16 v[94:97], v[162:165], v[232:235], v[94:97]
	v_mfma_f32_16x16x32_bf16 v[86:89], v[154:157], v[240:243], v[86:89]
	v_mfma_f32_16x16x32_bf16 v[78:81], v[162:165], v[240:243], v[78:81]
	s_setprio 0
	s_setprio 1
	v_mfma_f32_16x16x32_bf16 v[114:117], v[166:169], v[212:215], v[114:117]
	v_mfma_f32_16x16x32_bf16 v[106:109], v[188:191], v[212:215], v[106:109]
	v_mfma_f32_16x16x32_bf16 v[98:101], v[166:169], v[220:223], v[98:101]
	v_mfma_f32_16x16x32_bf16 v[90:93], v[188:191], v[220:223], v[90:93]
	v_mfma_f32_16x16x32_bf16 v[82:85], v[166:169], v[228:231], v[82:85]
	v_mfma_f32_16x16x32_bf16 v[74:77], v[188:191], v[228:231], v[74:77]
	v_mfma_f32_16x16x32_bf16 v[70:73], v[166:169], v[236:239], v[70:73]
	v_mfma_f32_16x16x32_bf16 v[66:69], v[188:191], v[236:239], v[66:69]
	v_mfma_f32_16x16x32_bf16 v[114:117], v[170:173], v[216:219], v[114:117]
	v_mfma_f32_16x16x32_bf16 v[106:109], v[192:195], v[216:219], v[106:109]
	v_mfma_f32_16x16x32_bf16 v[98:101], v[170:173], v[224:227], v[98:101]
	v_mfma_f32_16x16x32_bf16 v[90:93], v[192:195], v[224:227], v[90:93]
	v_mfma_f32_16x16x32_bf16 v[82:85], v[170:173], v[232:235], v[82:85]
	v_mfma_f32_16x16x32_bf16 v[74:77], v[192:195], v[232:235], v[74:77]
	v_mfma_f32_16x16x32_bf16 v[70:73], v[170:173], v[240:243], v[70:73]
	v_mfma_f32_16x16x32_bf16 v[66:69], v[192:195], v[240:243], v[66:69]
	s_setprio 0
	s_barrier
	s_add_i32 s34, s34, s41
	v_lshl_add_u64 v[148:149], s[26:27], 0, v[136:137]
	s_mov_b32 m0, s34
	ds_read_b128 v[212:215], v153 offset:16384
	ds_read_b128 v[216:219], v153 offset:17408
	ds_read_b128 v[220:223], v153 offset:18432
	ds_read_b128 v[224:227], v153 offset:19456
	ds_read_b128 v[228:231], v153 offset:20480
	ds_read_b128 v[232:235], v153 offset:21504
	ds_read_b128 v[236:239], v153 offset:22528
	ds_read_b128 v[240:243], v153 offset:23552
	global_load_lds_dwordx4 v[148:149], off
	s_add_i32 m0, s34, 0x2000
	s_add_u32 s34, s26, 0x40000
	v_lshl_add_u64 v[174:175], s[26:27], 0, v[132:133]
	s_addc_u32 s35, s27, 0
	s_add_i32 s63, s63, s41
	global_load_lds_dwordx4 v[174:175], off
	v_lshl_add_u64 v[206:207], s[34:35], 0, v[136:137]
	s_mov_b32 m0, s63
	v_lshl_add_u64 v[244:245], s[28:29], 0, v[134:135]
	global_load_lds_dwordx4 v[206:207], off
	v_lshl_add_u64 v[206:207], s[34:35], 0, v[132:133]
	s_add_i32 m0, s63, 0x2000
	s_nop 0
	global_load_lds_dwordx4 v[206:207], off
	v_lshl_add_u64 v[206:207], s[28:29], 0, v[138:139]
	s_mov_b32 m0, s43
	s_nop 0
	global_load_lds_dwordx4 v[206:207], off
	s_mov_b32 m0, s44
	s_nop 0
	global_load_lds_dwordx4 v[244:245], off
	s_waitcnt vmcnt(8)
	s_waitcnt lgkmcnt(0)
	s_barrier
	s_setprio 1
	s_waitcnt lgkmcnt(0)
	v_mfma_f32_16x16x32_bf16 v[62:65], v[144:147], v[212:215], v[62:65]
	v_mfma_f32_16x16x32_bf16 v[58:61], v[158:161], v[212:215], v[58:61]
	v_mfma_f32_16x16x32_bf16 v[54:57], v[144:147], v[220:223], v[54:57]
	v_mfma_f32_16x16x32_bf16 v[46:49], v[158:161], v[220:223], v[46:49]
	v_mfma_f32_16x16x32_bf16 v[38:41], v[144:147], v[228:231], v[38:41]
	v_mfma_f32_16x16x32_bf16 v[30:33], v[158:161], v[228:231], v[30:33]
	v_mfma_f32_16x16x32_bf16 v[18:21], v[144:147], v[236:239], v[18:21]
	v_mfma_f32_16x16x32_bf16 v[10:13], v[158:161], v[236:239], v[10:13]
	v_mfma_f32_16x16x32_bf16 v[62:65], v[154:157], v[216:219], v[62:65]
	v_mfma_f32_16x16x32_bf16 v[58:61], v[162:165], v[216:219], v[58:61]
	v_mfma_f32_16x16x32_bf16 v[54:57], v[154:157], v[224:227], v[54:57]
	v_mfma_f32_16x16x32_bf16 v[46:49], v[162:165], v[224:227], v[46:49]
	v_mfma_f32_16x16x32_bf16 v[38:41], v[154:157], v[232:235], v[38:41]
	v_mfma_f32_16x16x32_bf16 v[30:33], v[162:165], v[232:235], v[30:33]
	v_mfma_f32_16x16x32_bf16 v[18:21], v[154:157], v[240:243], v[18:21]
	v_mfma_f32_16x16x32_bf16 v[10:13], v[162:165], v[240:243], v[10:13]
	s_setprio 0
	s_setprio 1
	v_mfma_f32_16x16x32_bf16 v[50:53], v[166:169], v[212:215], v[50:53]
	v_mfma_f32_16x16x32_bf16 v[42:45], v[188:191], v[212:215], v[42:45]
	v_mfma_f32_16x16x32_bf16 v[34:37], v[166:169], v[220:223], v[34:37]
	v_mfma_f32_16x16x32_bf16 v[26:29], v[188:191], v[220:223], v[26:29]
	v_mfma_f32_16x16x32_bf16 v[22:25], v[166:169], v[228:231], v[22:25]
	v_mfma_f32_16x16x32_bf16 v[14:17], v[188:191], v[228:231], v[14:17]
	v_mfma_f32_16x16x32_bf16 v[6:9], v[166:169], v[236:239], v[6:9]
	v_mfma_f32_16x16x32_bf16 v[2:5], v[188:191], v[236:239], v[2:5]
	v_mfma_f32_16x16x32_bf16 v[50:53], v[170:173], v[216:219], v[50:53]
	v_mfma_f32_16x16x32_bf16 v[42:45], v[192:195], v[216:219], v[42:45]
	v_mfma_f32_16x16x32_bf16 v[34:37], v[170:173], v[224:227], v[34:37]
	v_mfma_f32_16x16x32_bf16 v[26:29], v[192:195], v[224:227], v[26:29]
	v_mfma_f32_16x16x32_bf16 v[22:25], v[170:173], v[232:235], v[22:25]
	v_mfma_f32_16x16x32_bf16 v[14:17], v[192:195], v[232:235], v[14:17]
	v_mfma_f32_16x16x32_bf16 v[6:9], v[170:173], v[240:243], v[6:9]
	v_mfma_f32_16x16x32_bf16 v[2:5], v[192:195], v[240:243], v[2:5]
	s_setprio 0
	s_barrier
	s_add_i32 s34, 0, 0x18000
	s_add_i32 s35, 0, 0x1c000
	v_add_u32_e32 v162, s34, v151
	v_add_u32_e32 v176, s35, v151
	ds_read_b128 v[144:147], v162
	ds_read_b128 v[154:157], v162 offset:1024
	ds_read_b128 v[158:161], v162 offset:2048
	ds_read_b128 v[162:165], v162 offset:3072
	ds_read_b128 v[166:169], v176
	ds_read_b128 v[170:173], v176 offset:1024
	ds_read_b128 v[188:191], v176 offset:2048
	ds_read_b128 v[192:195], v176 offset:3072
	s_add_u32 s28, s28, 0x40000
	s_addc_u32 s29, s29, 0
	s_mov_b32 m0, s45
	v_lshl_add_u64 v[246:247], s[28:29], 0, v[138:139]
	ds_read_b128 v[212:215], v153 offset:32768
	ds_read_b128 v[216:219], v153 offset:33792
	ds_read_b128 v[220:223], v153 offset:34816
	ds_read_b128 v[224:227], v153 offset:35840
	ds_read_b128 v[228:231], v153 offset:36864
	ds_read_b128 v[232:235], v153 offset:37888
	ds_read_b128 v[236:239], v153 offset:38912
	ds_read_b128 v[240:243], v153 offset:39936
	global_load_lds_dwordx4 v[246:247], off
	v_lshl_add_u64 v[246:247], s[28:29], 0, v[134:135]
	s_mov_b32 m0, s57
	s_nop 0
	global_load_lds_dwordx4 v[246:247], off
	s_waitcnt vmcnt(8)
	s_waitcnt lgkmcnt(0)
	s_barrier
	s_setprio 1
	s_waitcnt lgkmcnt(0)
	v_mfma_f32_16x16x32_bf16 v[126:129], v[144:147], v[212:215], v[126:129]
	v_mfma_f32_16x16x32_bf16 v[122:125], v[158:161], v[212:215], v[122:125]
	v_mfma_f32_16x16x32_bf16 v[118:121], v[144:147], v[220:223], v[118:121]
	v_mfma_f32_16x16x32_bf16 v[110:113], v[158:161], v[220:223], v[110:113]
	v_mfma_f32_16x16x32_bf16 v[102:105], v[144:147], v[228:231], v[102:105]
	v_mfma_f32_16x16x32_bf16 v[94:97], v[158:161], v[228:231], v[94:97]
	v_mfma_f32_16x16x32_bf16 v[86:89], v[144:147], v[236:239], v[86:89]
	v_mfma_f32_16x16x32_bf16 v[78:81], v[158:161], v[236:239], v[78:81]
	v_mfma_f32_16x16x32_bf16 v[126:129], v[154:157], v[216:219], v[126:129]
	v_mfma_f32_16x16x32_bf16 v[122:125], v[162:165], v[216:219], v[122:125]
	v_mfma_f32_16x16x32_bf16 v[118:121], v[154:157], v[224:227], v[118:121]
	v_mfma_f32_16x16x32_bf16 v[110:113], v[162:165], v[224:227], v[110:113]
	v_mfma_f32_16x16x32_bf16 v[102:105], v[154:157], v[232:235], v[102:105]
	v_mfma_f32_16x16x32_bf16 v[94:97], v[162:165], v[232:235], v[94:97]
	v_mfma_f32_16x16x32_bf16 v[86:89], v[154:157], v[240:243], v[86:89]
	v_mfma_f32_16x16x32_bf16 v[78:81], v[162:165], v[240:243], v[78:81]
	s_setprio 0
	s_setprio 1
	v_mfma_f32_16x16x32_bf16 v[114:117], v[166:169], v[212:215], v[114:117]
	v_mfma_f32_16x16x32_bf16 v[106:109], v[188:191], v[212:215], v[106:109]
	v_mfma_f32_16x16x32_bf16 v[98:101], v[166:169], v[220:223], v[98:101]
	v_mfma_f32_16x16x32_bf16 v[90:93], v[188:191], v[220:223], v[90:93]
	v_mfma_f32_16x16x32_bf16 v[82:85], v[166:169], v[228:231], v[82:85]
	v_mfma_f32_16x16x32_bf16 v[74:77], v[188:191], v[228:231], v[74:77]
	v_mfma_f32_16x16x32_bf16 v[70:73], v[166:169], v[236:239], v[70:73]
	v_mfma_f32_16x16x32_bf16 v[66:69], v[188:191], v[236:239], v[66:69]
	v_mfma_f32_16x16x32_bf16 v[114:117], v[170:173], v[216:219], v[114:117]
	v_mfma_f32_16x16x32_bf16 v[106:109], v[192:195], v[216:219], v[106:109]
	v_mfma_f32_16x16x32_bf16 v[98:101], v[170:173], v[224:227], v[98:101]
	v_mfma_f32_16x16x32_bf16 v[90:93], v[192:195], v[224:227], v[90:93]
	v_mfma_f32_16x16x32_bf16 v[82:85], v[170:173], v[232:235], v[82:85]
	v_mfma_f32_16x16x32_bf16 v[74:77], v[192:195], v[232:235], v[74:77]
	v_mfma_f32_16x16x32_bf16 v[70:73], v[170:173], v[240:243], v[70:73]
	v_mfma_f32_16x16x32_bf16 v[66:69], v[192:195], v[240:243], v[66:69]
	s_setprio 0
	s_barrier
	s_add_i32 s28, s34, s41
	v_lshl_add_u64 v[148:149], v[148:149], 0, s[68:69]
	s_mov_b32 m0, s28
	ds_read_b128 v[212:215], v153 offset:49152
	ds_read_b128 v[216:219], v153 offset:50176
	ds_read_b128 v[220:223], v153 offset:51200
	ds_read_b128 v[224:227], v153 offset:52224
	ds_read_b128 v[228:231], v153 offset:53248
	ds_read_b128 v[232:235], v153 offset:54272
	ds_read_b128 v[236:239], v153 offset:55296
	ds_read_b128 v[240:243], v153 offset:56320
	global_load_lds_dwordx4 v[148:149], off
	s_add_i32 m0, s28, 0x2000
	s_add_u32 s26, s26, 0x40080
	v_lshl_add_u64 v[148:149], v[174:175], 0, s[68:69]
	s_addc_u32 s27, s27, 0
	s_add_i32 s28, s35, s41
	global_load_lds_dwordx4 v[148:149], off
	v_lshl_add_u64 v[148:149], s[26:27], 0, v[136:137]
	s_mov_b32 m0, s28
	s_nop 0
	global_load_lds_dwordx4 v[148:149], off
	v_lshl_add_u64 v[148:149], s[26:27], 0, v[132:133]
	s_add_i32 m0, s28, 0x2000
	s_nop 0
	global_load_lds_dwordx4 v[148:149], off
	v_lshl_add_u64 v[148:149], v[206:207], 0, s[68:69]
	s_mov_b32 m0, s16
	s_nop 0
	global_load_lds_dwordx4 v[148:149], off
	v_lshl_add_u64 v[148:149], v[244:245], 0, s[68:69]
	s_mov_b32 m0, s51
	s_nop 0
	global_load_lds_dwordx4 v[148:149], off
	s_waitcnt vmcnt(8)
	s_waitcnt lgkmcnt(0)
	s_barrier
	s_setprio 1
	s_waitcnt lgkmcnt(0)
	v_mfma_f32_16x16x32_bf16 v[62:65], v[144:147], v[212:215], v[62:65]
	v_mfma_f32_16x16x32_bf16 v[58:61], v[158:161], v[212:215], v[58:61]
	v_mfma_f32_16x16x32_bf16 v[54:57], v[144:147], v[220:223], v[54:57]
	v_mfma_f32_16x16x32_bf16 v[46:49], v[158:161], v[220:223], v[46:49]
	v_mfma_f32_16x16x32_bf16 v[38:41], v[144:147], v[228:231], v[38:41]
	v_mfma_f32_16x16x32_bf16 v[30:33], v[158:161], v[228:231], v[30:33]
	v_mfma_f32_16x16x32_bf16 v[18:21], v[144:147], v[236:239], v[18:21]
	v_mfma_f32_16x16x32_bf16 v[10:13], v[158:161], v[236:239], v[10:13]
	v_mfma_f32_16x16x32_bf16 v[62:65], v[154:157], v[216:219], v[62:65]
	v_mfma_f32_16x16x32_bf16 v[58:61], v[162:165], v[216:219], v[58:61]
	v_mfma_f32_16x16x32_bf16 v[54:57], v[154:157], v[224:227], v[54:57]
	v_mfma_f32_16x16x32_bf16 v[46:49], v[162:165], v[224:227], v[46:49]
	v_mfma_f32_16x16x32_bf16 v[38:41], v[154:157], v[232:235], v[38:41]
	v_mfma_f32_16x16x32_bf16 v[30:33], v[162:165], v[232:235], v[30:33]
	v_mfma_f32_16x16x32_bf16 v[18:21], v[154:157], v[240:243], v[18:21]
	v_mfma_f32_16x16x32_bf16 v[10:13], v[162:165], v[240:243], v[10:13]
	s_setprio 0
	s_setprio 1
	v_mfma_f32_16x16x32_bf16 v[50:53], v[166:169], v[212:215], v[50:53]
	v_mfma_f32_16x16x32_bf16 v[42:45], v[188:191], v[212:215], v[42:45]
	v_mfma_f32_16x16x32_bf16 v[34:37], v[166:169], v[220:223], v[34:37]
	v_mfma_f32_16x16x32_bf16 v[26:29], v[188:191], v[220:223], v[26:29]
	v_mfma_f32_16x16x32_bf16 v[22:25], v[166:169], v[228:231], v[22:25]
	v_mfma_f32_16x16x32_bf16 v[14:17], v[188:191], v[228:231], v[14:17]
	v_mfma_f32_16x16x32_bf16 v[6:9], v[166:169], v[236:239], v[6:9]
	v_mfma_f32_16x16x32_bf16 v[2:5], v[188:191], v[236:239], v[2:5]
	v_mfma_f32_16x16x32_bf16 v[50:53], v[170:173], v[216:219], v[50:53]
	v_mfma_f32_16x16x32_bf16 v[42:45], v[192:195], v[216:219], v[42:45]
	v_mfma_f32_16x16x32_bf16 v[34:37], v[170:173], v[224:227], v[34:37]
	v_mfma_f32_16x16x32_bf16 v[26:29], v[192:195], v[224:227], v[26:29]
	v_mfma_f32_16x16x32_bf16 v[22:25], v[170:173], v[232:235], v[22:25]
	v_mfma_f32_16x16x32_bf16 v[14:17], v[192:195], v[232:235], v[14:17]
	v_mfma_f32_16x16x32_bf16 v[6:9], v[170:173], v[240:243], v[6:9]
	v_mfma_f32_16x16x32_bf16 v[2:5], v[192:195], v[240:243], v[2:5]
	s_add_i32 s31, s31, 2
	s_add_u32 s24, s24, 0x100
	s_addc_u32 s25, s25, 0
	s_add_u32 s23, s23, 0x100
	s_addc_u32 s30, s30, 0
	s_setprio 0
	s_barrier
	s_cmp_gt_u32 s31, 13
	s_cbranch_scc0 .LBB0_223
	s_and_b64 vcc, exec, s[6:7]
	s_cbranch_vccz .LBB0_226
	s_barrier

.LBB0_257:
	s_add_u32 s26, s24, 0xfffc0080
	s_addc_u32 s27, s25, -1
	s_add_i32 s39, 0, 0x10000
	s_cmp_eq_u32 s38, 12
	s_cselect_b32 s29, s30, s27
	s_cselect_b32 s28, s31, s26
	s_cselect_b32 s27, s34, s37
	s_cselect_b32 s26, s35, s36
	s_add_i32 s73, 0, 0x14000
	v_add_u32_e32 v158, s39, v176
	v_add_u32_e32 v174, s73, v176
	ds_read_b128 v[146:149], v158
	ds_read_b128 v[150:153], v158 offset:1024
	ds_read_b128 v[154:157], v158 offset:2048
	ds_read_b128 v[158:161], v158 offset:3072
	ds_read_b128 v[162:165], v174
	ds_read_b128 v[166:169], v174 offset:1024
	ds_read_b128 v[170:173], v174 offset:2048
	ds_read_b128 v[188:191], v174 offset:3072
	v_lshl_add_u64 v[174:175], s[24:25], 0, v[142:143]
	s_add_i32 m0, s23, 0xc000
	ds_read_b128 v[212:215], v192
	ds_read_b128 v[216:219], v192 offset:1024
	ds_read_b128 v[220:223], v192 offset:2048
	ds_read_b128 v[224:227], v192 offset:3072
	ds_read_b128 v[228:231], v192 offset:4096
	ds_read_b128 v[232:235], v192 offset:5120
	ds_read_b128 v[236:239], v192 offset:6144
	ds_read_b128 v[240:243], v192 offset:7168
	global_load_lds_dwordx4 v[174:175], off
	v_lshl_add_u64 v[174:175], s[24:25], 0, v[144:145]
	s_add_i32 m0, s23, 0xe000
	s_nop 0
	global_load_lds_dwordx4 v[174:175], off
	s_waitcnt vmcnt(8)
	s_waitcnt lgkmcnt(0)
	s_barrier
	s_setprio 1
	s_waitcnt lgkmcnt(0)
	v_mfma_f32_16x16x32_bf16 v[126:129], v[146:149], v[212:215], v[126:129]
	v_mfma_f32_16x16x32_bf16 v[122:125], v[154:157], v[212:215], v[122:125]
	v_mfma_f32_16x16x32_bf16 v[118:121], v[146:149], v[220:223], v[118:121]
	v_mfma_f32_16x16x32_bf16 v[110:113], v[154:157], v[220:223], v[110:113]
	v_mfma_f32_16x16x32_bf16 v[102:105], v[146:149], v[228:231], v[102:105]
	v_mfma_f32_16x16x32_bf16 v[94:97], v[154:157], v[228:231], v[94:97]
	v_mfma_f32_16x16x32_bf16 v[86:89], v[146:149], v[236:239], v[86:89]
	v_mfma_f32_16x16x32_bf16 v[78:81], v[154:157], v[236:239], v[78:81]
	v_mfma_f32_16x16x32_bf16 v[126:129], v[150:153], v[216:219], v[126:129]
	v_mfma_f32_16x16x32_bf16 v[122:125], v[158:161], v[216:219], v[122:125]
	v_mfma_f32_16x16x32_bf16 v[118:121], v[150:153], v[224:227], v[118:121]
	v_mfma_f32_16x16x32_bf16 v[110:113], v[158:161], v[224:227], v[110:113]
	v_mfma_f32_16x16x32_bf16 v[102:105], v[150:153], v[232:235], v[102:105]
	v_mfma_f32_16x16x32_bf16 v[94:97], v[158:161], v[232:235], v[94:97]
	v_mfma_f32_16x16x32_bf16 v[86:89], v[150:153], v[240:243], v[86:89]
	v_mfma_f32_16x16x32_bf16 v[78:81], v[158:161], v[240:243], v[78:81]
	s_setprio 0
	s_setprio 1
	v_mfma_f32_16x16x32_bf16 v[114:117], v[162:165], v[212:215], v[114:117]
	v_mfma_f32_16x16x32_bf16 v[106:109], v[170:173], v[212:215], v[106:109]
	v_mfma_f32_16x16x32_bf16 v[98:101], v[162:165], v[220:223], v[98:101]
	v_mfma_f32_16x16x32_bf16 v[90:93], v[170:173], v[220:223], v[90:93]
	v_mfma_f32_16x16x32_bf16 v[82:85], v[162:165], v[228:231], v[82:85]
	v_mfma_f32_16x16x32_bf16 v[74:77], v[170:173], v[228:231], v[74:77]
	v_mfma_f32_16x16x32_bf16 v[70:73], v[162:165], v[236:239], v[70:73]
	v_mfma_f32_16x16x32_bf16 v[66:69], v[170:173], v[236:239], v[66:69]
	v_mfma_f32_16x16x32_bf16 v[114:117], v[166:169], v[216:219], v[114:117]
	v_mfma_f32_16x16x32_bf16 v[106:109], v[188:191], v[216:219], v[106:109]
	v_mfma_f32_16x16x32_bf16 v[98:101], v[166:169], v[224:227], v[98:101]
	v_mfma_f32_16x16x32_bf16 v[90:93], v[188:191], v[224:227], v[90:93]
	v_mfma_f32_16x16x32_bf16 v[82:85], v[166:169], v[232:235], v[82:85]
	v_mfma_f32_16x16x32_bf16 v[74:77], v[188:191], v[232:235], v[74:77]
	v_mfma_f32_16x16x32_bf16 v[70:73], v[166:169], v[240:243], v[70:73]
	v_mfma_f32_16x16x32_bf16 v[66:69], v[188:191], v[240:243], v[66:69]
	s_setprio 0
	s_barrier
	s_add_i32 s39, s39, s41
	v_lshl_add_u64 v[174:175], s[26:27], 0, v[136:137]
	s_mov_b32 m0, s39
	ds_read_b128 v[212:215], v192 offset:16384
	ds_read_b128 v[216:219], v192 offset:17408
	ds_read_b128 v[220:223], v192 offset:18432
	ds_read_b128 v[224:227], v192 offset:19456
	ds_read_b128 v[228:231], v192 offset:20480
	ds_read_b128 v[232:235], v192 offset:21504
	ds_read_b128 v[236:239], v192 offset:22528
	ds_read_b128 v[240:243], v192 offset:23552
	global_load_lds_dwordx4 v[174:175], off
	s_add_i32 m0, s39, 0x2000
	s_add_u32 s74, s26, 0x40000
	v_lshl_add_u64 v[194:195], s[26:27], 0, v[132:133]
	s_addc_u32 s75, s27, 0
	s_add_i32 s39, s73, s41
	global_load_lds_dwordx4 v[194:195], off
	v_lshl_add_u64 v[206:207], s[74:75], 0, v[136:137]
	s_mov_b32 m0, s39
	v_lshl_add_u64 v[244:245], s[28:29], 0, v[134:135]
	global_load_lds_dwordx4 v[206:207], off
	v_lshl_add_u64 v[206:207], s[74:75], 0, v[132:133]
	s_add_i32 m0, s39, 0x2000
	s_nop 0
	global_load_lds_dwordx4 v[206:207], off
	v_lshl_add_u64 v[206:207], s[28:29], 0, v[138:139]
	s_mov_b32 m0, s23
	s_nop 0
	global_load_lds_dwordx4 v[206:207], off
	s_mov_b32 m0, s42
	s_nop 0
	global_load_lds_dwordx4 v[244:245], off
	s_waitcnt vmcnt(8)
	s_waitcnt lgkmcnt(0)
	s_barrier
	s_setprio 1
	s_waitcnt lgkmcnt(0)
	v_mfma_f32_16x16x32_bf16 v[62:65], v[146:149], v[212:215], v[62:65]
	v_mfma_f32_16x16x32_bf16 v[58:61], v[154:157], v[212:215], v[58:61]
	v_mfma_f32_16x16x32_bf16 v[54:57], v[146:149], v[220:223], v[54:57]
	v_mfma_f32_16x16x32_bf16 v[46:49], v[154:157], v[220:223], v[46:49]
	v_mfma_f32_16x16x32_bf16 v[38:41], v[146:149], v[228:231], v[38:41]
	v_mfma_f32_16x16x32_bf16 v[30:33], v[154:157], v[228:231], v[30:33]
	v_mfma_f32_16x16x32_bf16 v[22:25], v[146:149], v[236:239], v[22:25]
	v_mfma_f32_16x16x32_bf16 v[14:17], v[154:157], v[236:239], v[14:17]
	v_mfma_f32_16x16x32_bf16 v[62:65], v[150:153], v[216:219], v[62:65]
	v_mfma_f32_16x16x32_bf16 v[58:61], v[158:161], v[216:219], v[58:61]
	v_mfma_f32_16x16x32_bf16 v[54:57], v[150:153], v[224:227], v[54:57]
	v_mfma_f32_16x16x32_bf16 v[46:49], v[158:161], v[224:227], v[46:49]
	v_mfma_f32_16x16x32_bf16 v[38:41], v[150:153], v[232:235], v[38:41]
	v_mfma_f32_16x16x32_bf16 v[30:33], v[158:161], v[232:235], v[30:33]
	v_mfma_f32_16x16x32_bf16 v[22:25], v[150:153], v[240:243], v[22:25]
	v_mfma_f32_16x16x32_bf16 v[14:17], v[158:161], v[240:243], v[14:17]
	s_setprio 0
	s_setprio 1
	v_mfma_f32_16x16x32_bf16 v[50:53], v[162:165], v[212:215], v[50:53]
	v_mfma_f32_16x16x32_bf16 v[42:45], v[170:173], v[212:215], v[42:45]
	v_mfma_f32_16x16x32_bf16 v[34:37], v[162:165], v[220:223], v[34:37]
	v_mfma_f32_16x16x32_bf16 v[26:29], v[170:173], v[220:223], v[26:29]
	v_mfma_f32_16x16x32_bf16 v[18:21], v[162:165], v[228:231], v[18:21]
	v_mfma_f32_16x16x32_bf16 v[10:13], v[170:173], v[228:231], v[10:13]
	v_mfma_f32_16x16x32_bf16 v[6:9], v[162:165], v[236:239], v[6:9]
	v_mfma_f32_16x16x32_bf16 v[2:5], v[170:173], v[236:239], v[2:5]
	v_mfma_f32_16x16x32_bf16 v[50:53], v[166:169], v[216:219], v[50:53]
	v_mfma_f32_16x16x32_bf16 v[42:45], v[188:191], v[216:219], v[42:45]
	v_mfma_f32_16x16x32_bf16 v[34:37], v[166:169], v[224:227], v[34:37]
	v_mfma_f32_16x16x32_bf16 v[26:29], v[188:191], v[224:227], v[26:29]
	v_mfma_f32_16x16x32_bf16 v[18:21], v[166:169], v[232:235], v[18:21]
	v_mfma_f32_16x16x32_bf16 v[10:13], v[188:191], v[232:235], v[10:13]
	v_mfma_f32_16x16x32_bf16 v[6:9], v[166:169], v[240:243], v[6:9]
	v_mfma_f32_16x16x32_bf16 v[2:5], v[188:191], v[240:243], v[2:5]
	s_setprio 0
	s_barrier
	s_add_i32 s39, 0, 0x18000
	s_add_i32 s73, 0, 0x1c000
	v_add_u32_e32 v158, s39, v176
	v_add_u32_e32 v188, s73, v176
	ds_read_b128 v[146:149], v158
	ds_read_b128 v[150:153], v158 offset:1024
	ds_read_b128 v[154:157], v158 offset:2048
	ds_read_b128 v[158:161], v158 offset:3072
	ds_read_b128 v[162:165], v188
	ds_read_b128 v[166:169], v188 offset:1024
	ds_read_b128 v[170:173], v188 offset:2048
	ds_read_b128 v[188:191], v188 offset:3072
	s_add_u32 s28, s28, 0x40000
	s_addc_u32 s29, s29, 0
	s_mov_b32 m0, s43
	v_lshl_add_u64 v[246:247], s[28:29], 0, v[138:139]
	ds_read_b128 v[212:215], v192 offset:32768
	ds_read_b128 v[216:219], v192 offset:33792
	ds_read_b128 v[220:223], v192 offset:34816
	ds_read_b128 v[224:227], v192 offset:35840
	ds_read_b128 v[228:231], v192 offset:36864
	ds_read_b128 v[232:235], v192 offset:37888
	ds_read_b128 v[236:239], v192 offset:38912
	ds_read_b128 v[240:243], v192 offset:39936
	global_load_lds_dwordx4 v[246:247], off
	v_lshl_add_u64 v[246:247], s[28:29], 0, v[134:135]
	s_mov_b32 m0, s44
	s_nop 0
	global_load_lds_dwordx4 v[246:247], off
	s_waitcnt vmcnt(8)
	s_waitcnt lgkmcnt(0)
	s_barrier
	s_setprio 1
	s_waitcnt lgkmcnt(0)
	v_mfma_f32_16x16x32_bf16 v[126:129], v[146:149], v[212:215], v[126:129]
	v_mfma_f32_16x16x32_bf16 v[122:125], v[154:157], v[212:215], v[122:125]
	v_mfma_f32_16x16x32_bf16 v[118:121], v[146:149], v[220:223], v[118:121]
	v_mfma_f32_16x16x32_bf16 v[110:113], v[154:157], v[220:223], v[110:113]
	v_mfma_f32_16x16x32_bf16 v[102:105], v[146:149], v[228:231], v[102:105]
	v_mfma_f32_16x16x32_bf16 v[94:97], v[154:157], v[228:231], v[94:97]
	v_mfma_f32_16x16x32_bf16 v[86:89], v[146:149], v[236:239], v[86:89]
	v_mfma_f32_16x16x32_bf16 v[78:81], v[154:157], v[236:239], v[78:81]
	v_mfma_f32_16x16x32_bf16 v[126:129], v[150:153], v[216:219], v[126:129]
	v_mfma_f32_16x16x32_bf16 v[122:125], v[158:161], v[216:219], v[122:125]
	v_mfma_f32_16x16x32_bf16 v[118:121], v[150:153], v[224:227], v[118:121]
	v_mfma_f32_16x16x32_bf16 v[110:113], v[158:161], v[224:227], v[110:113]
	v_mfma_f32_16x16x32_bf16 v[102:105], v[150:153], v[232:235], v[102:105]
	v_mfma_f32_16x16x32_bf16 v[94:97], v[158:161], v[232:235], v[94:97]
	v_mfma_f32_16x16x32_bf16 v[86:89], v[150:153], v[240:243], v[86:89]
	v_mfma_f32_16x16x32_bf16 v[78:81], v[158:161], v[240:243], v[78:81]
	s_setprio 0
	s_setprio 1
	v_mfma_f32_16x16x32_bf16 v[114:117], v[162:165], v[212:215], v[114:117]
	v_mfma_f32_16x16x32_bf16 v[106:109], v[170:173], v[212:215], v[106:109]
	v_mfma_f32_16x16x32_bf16 v[98:101], v[162:165], v[220:223], v[98:101]
	v_mfma_f32_16x16x32_bf16 v[90:93], v[170:173], v[220:223], v[90:93]
	v_mfma_f32_16x16x32_bf16 v[82:85], v[162:165], v[228:231], v[82:85]
	v_mfma_f32_16x16x32_bf16 v[74:77], v[170:173], v[228:231], v[74:77]
	v_mfma_f32_16x16x32_bf16 v[70:73], v[162:165], v[236:239], v[70:73]
	v_mfma_f32_16x16x32_bf16 v[66:69], v[170:173], v[236:239], v[66:69]
	v_mfma_f32_16x16x32_bf16 v[114:117], v[166:169], v[216:219], v[114:117]
	v_mfma_f32_16x16x32_bf16 v[106:109], v[188:191], v[216:219], v[106:109]
	v_mfma_f32_16x16x32_bf16 v[98:101], v[166:169], v[224:227], v[98:101]
	v_mfma_f32_16x16x32_bf16 v[90:93], v[188:191], v[224:227], v[90:93]
	v_mfma_f32_16x16x32_bf16 v[82:85], v[166:169], v[232:235], v[82:85]
	v_mfma_f32_16x16x32_bf16 v[74:77], v[188:191], v[232:235], v[74:77]
	v_mfma_f32_16x16x32_bf16 v[70:73], v[166:169], v[240:243], v[70:73]
	v_mfma_f32_16x16x32_bf16 v[66:69], v[188:191], v[240:243], v[66:69]
	s_setprio 0
	s_barrier
	s_add_i32 s28, s39, s41
	v_lshl_add_u64 v[174:175], v[174:175], 0, s[68:69]
	s_mov_b32 m0, s28
	ds_read_b128 v[212:215], v192 offset:49152
	ds_read_b128 v[216:219], v192 offset:50176
	ds_read_b128 v[220:223], v192 offset:51200
	ds_read_b128 v[224:227], v192 offset:52224
	ds_read_b128 v[228:231], v192 offset:53248
	ds_read_b128 v[232:235], v192 offset:54272
	ds_read_b128 v[236:239], v192 offset:55296
	ds_read_b128 v[240:243], v192 offset:56320
	global_load_lds_dwordx4 v[174:175], off
	s_add_i32 m0, s28, 0x2000
	s_add_u32 s26, s26, 0x40080
	v_lshl_add_u64 v[174:175], v[194:195], 0, s[68:69]
	s_addc_u32 s27, s27, 0
	s_add_i32 s28, s73, s41
	global_load_lds_dwordx4 v[174:175], off
	v_lshl_add_u64 v[174:175], s[26:27], 0, v[136:137]
	s_mov_b32 m0, s28
	s_nop 0
	global_load_lds_dwordx4 v[174:175], off
	v_lshl_add_u64 v[174:175], s[26:27], 0, v[132:133]
	s_add_i32 m0, s28, 0x2000
	s_nop 0
	global_load_lds_dwordx4 v[174:175], off
	v_lshl_add_u64 v[174:175], v[206:207], 0, s[68:69]
	s_mov_b32 m0, s45
	s_nop 0
	global_load_lds_dwordx4 v[174:175], off
	v_lshl_add_u64 v[174:175], v[244:245], 0, s[68:69]
	s_mov_b32 m0, s51
	s_nop 0
	global_load_lds_dwordx4 v[174:175], off
	s_waitcnt vmcnt(8)
	s_waitcnt lgkmcnt(0)
	s_barrier
	s_setprio 1
	s_waitcnt lgkmcnt(0)
	v_mfma_f32_16x16x32_bf16 v[62:65], v[146:149], v[212:215], v[62:65]
	v_mfma_f32_16x16x32_bf16 v[58:61], v[154:157], v[212:215], v[58:61]
	v_mfma_f32_16x16x32_bf16 v[54:57], v[146:149], v[220:223], v[54:57]
	v_mfma_f32_16x16x32_bf16 v[46:49], v[154:157], v[220:223], v[46:49]
	v_mfma_f32_16x16x32_bf16 v[38:41], v[146:149], v[228:231], v[38:41]
	v_mfma_f32_16x16x32_bf16 v[30:33], v[154:157], v[228:231], v[30:33]
	v_mfma_f32_16x16x32_bf16 v[22:25], v[146:149], v[236:239], v[22:25]
	v_mfma_f32_16x16x32_bf16 v[14:17], v[154:157], v[236:239], v[14:17]
	v_mfma_f32_16x16x32_bf16 v[62:65], v[150:153], v[216:219], v[62:65]
	v_mfma_f32_16x16x32_bf16 v[58:61], v[158:161], v[216:219], v[58:61]
	v_mfma_f32_16x16x32_bf16 v[54:57], v[150:153], v[224:227], v[54:57]
	v_mfma_f32_16x16x32_bf16 v[46:49], v[158:161], v[224:227], v[46:49]
	v_mfma_f32_16x16x32_bf16 v[38:41], v[150:153], v[232:235], v[38:41]
	v_mfma_f32_16x16x32_bf16 v[30:33], v[158:161], v[232:235], v[30:33]
	v_mfma_f32_16x16x32_bf16 v[22:25], v[150:153], v[240:243], v[22:25]
	v_mfma_f32_16x16x32_bf16 v[14:17], v[158:161], v[240:243], v[14:17]
	s_setprio 0
	s_setprio 1
	v_mfma_f32_16x16x32_bf16 v[50:53], v[162:165], v[212:215], v[50:53]
	v_mfma_f32_16x16x32_bf16 v[42:45], v[170:173], v[212:215], v[42:45]
	v_mfma_f32_16x16x32_bf16 v[34:37], v[162:165], v[220:223], v[34:37]
	v_mfma_f32_16x16x32_bf16 v[26:29], v[170:173], v[220:223], v[26:29]
	v_mfma_f32_16x16x32_bf16 v[18:21], v[162:165], v[228:231], v[18:21]
	v_mfma_f32_16x16x32_bf16 v[10:13], v[170:173], v[228:231], v[10:13]
	v_mfma_f32_16x16x32_bf16 v[6:9], v[162:165], v[236:239], v[6:9]
	v_mfma_f32_16x16x32_bf16 v[2:5], v[170:173], v[236:239], v[2:5]
	v_mfma_f32_16x16x32_bf16 v[50:53], v[166:169], v[216:219], v[50:53]
	v_mfma_f32_16x16x32_bf16 v[42:45], v[188:191], v[216:219], v[42:45]
	v_mfma_f32_16x16x32_bf16 v[34:37], v[166:169], v[224:227], v[34:37]
	v_mfma_f32_16x16x32_bf16 v[26:29], v[188:191], v[224:227], v[26:29]
	v_mfma_f32_16x16x32_bf16 v[18:21], v[166:169], v[232:235], v[18:21]
	v_mfma_f32_16x16x32_bf16 v[10:13], v[188:191], v[232:235], v[10:13]
	v_mfma_f32_16x16x32_bf16 v[6:9], v[166:169], v[240:243], v[6:9]
	v_mfma_f32_16x16x32_bf16 v[2:5], v[188:191], v[240:243], v[2:5]
	s_add_i32 s38, s38, 2
	s_add_u32 s24, s24, 0x100
	s_addc_u32 s25, s25, 0
	s_add_u32 s36, s36, 0x100
	s_addc_u32 s37, s37, 0
	s_setprio 0
	s_barrier
	s_cmp_gt_u32 s38, 13
	s_cbranch_scc0 .LBB0_257
	s_and_b64 vcc, exec, s[58:59]
	s_cbranch_vccz .LBB0_260
	s_barrier

.LBB0_287:
	s_add_u32 s6, s24, 0xfffc0080
	s_addc_u32 s7, s25, -1
	s_add_i32 s37, 0, 0x10000
	s_cmp_eq_u32 s36, 12
	s_cselect_b32 s27, s13, s7
	s_cselect_b32 s26, s23, s6
	v_add_u32_e32 v152, s37, v156
	s_cselect_b32 s7, s30, s35
	s_cselect_b32 s6, s31, s34
	s_add_i32 s73, 0, 0x14000
	ds_read_b128 v[144:147], v152
	ds_read_b128 v[148:151], v152 offset:1024
	ds_read_b128 v[164:167], v152 offset:2048
	ds_read_b128 v[168:171], v152 offset:3072
	v_add_u32_e32 v152, s73, v156
	ds_read_b128 v[172:175], v152
	ds_read_b128 v[188:191], v152 offset:1024
	ds_read_b128 v[192:195], v152 offset:2048
	ds_read_b128 v[212:215], v152 offset:3072
	v_lshl_add_u64 v[152:153], s[24:25], 0, v[140:141]
	s_add_i32 m0, s57, 0xc000
	ds_read_b128 v[216:219], v161
	ds_read_b128 v[220:223], v161 offset:1024
	ds_read_b128 v[224:227], v161 offset:2048
	ds_read_b128 v[228:231], v161 offset:3072
	ds_read_b128 v[232:235], v161 offset:4096
	ds_read_b128 v[236:239], v161 offset:5120
	ds_read_b128 v[240:243], v161 offset:6144
	ds_read_b128 v[244:247], v161 offset:7168
	global_load_lds_dwordx4 v[152:153], off
	v_lshl_add_u64 v[152:153], s[24:25], 0, v[142:143]
	s_add_i32 m0, s57, 0xe000
	s_nop 0
	global_load_lds_dwordx4 v[152:153], off
	s_waitcnt vmcnt(8)
	s_waitcnt lgkmcnt(0)
	s_barrier
	s_setprio 1
	s_waitcnt lgkmcnt(0)
	v_mfma_f32_16x16x32_bf16 v[126:129], v[144:147], v[216:219], v[126:129]
	v_mfma_f32_16x16x32_bf16 v[122:125], v[164:167], v[216:219], v[122:125]
	v_mfma_f32_16x16x32_bf16 v[118:121], v[144:147], v[224:227], v[118:121]
	v_mfma_f32_16x16x32_bf16 v[110:113], v[164:167], v[224:227], v[110:113]
	v_mfma_f32_16x16x32_bf16 v[102:105], v[144:147], v[232:235], v[102:105]
	v_mfma_f32_16x16x32_bf16 v[94:97], v[164:167], v[232:235], v[94:97]
	v_mfma_f32_16x16x32_bf16 v[86:89], v[144:147], v[240:243], v[86:89]
	v_mfma_f32_16x16x32_bf16 v[78:81], v[164:167], v[240:243], v[78:81]
	v_mfma_f32_16x16x32_bf16 v[126:129], v[148:151], v[220:223], v[126:129]
	v_mfma_f32_16x16x32_bf16 v[122:125], v[168:171], v[220:223], v[122:125]
	v_mfma_f32_16x16x32_bf16 v[118:121], v[148:151], v[228:231], v[118:121]
	v_mfma_f32_16x16x32_bf16 v[110:113], v[168:171], v[228:231], v[110:113]
	v_mfma_f32_16x16x32_bf16 v[102:105], v[148:151], v[236:239], v[102:105]
	v_mfma_f32_16x16x32_bf16 v[94:97], v[168:171], v[236:239], v[94:97]
	v_mfma_f32_16x16x32_bf16 v[86:89], v[148:151], v[244:247], v[86:89]
	v_mfma_f32_16x16x32_bf16 v[78:81], v[168:171], v[244:247], v[78:81]
	s_setprio 0
	s_setprio 1
	v_mfma_f32_16x16x32_bf16 v[114:117], v[172:175], v[216:219], v[114:117]
	v_mfma_f32_16x16x32_bf16 v[106:109], v[192:195], v[216:219], v[106:109]
	v_mfma_f32_16x16x32_bf16 v[98:101], v[172:175], v[224:227], v[98:101]
	v_mfma_f32_16x16x32_bf16 v[90:93], v[192:195], v[224:227], v[90:93]
	v_mfma_f32_16x16x32_bf16 v[82:85], v[172:175], v[232:235], v[82:85]
	v_mfma_f32_16x16x32_bf16 v[74:77], v[192:195], v[232:235], v[74:77]
	v_mfma_f32_16x16x32_bf16 v[70:73], v[172:175], v[240:243], v[70:73]
	v_mfma_f32_16x16x32_bf16 v[66:69], v[192:195], v[240:243], v[66:69]
	v_mfma_f32_16x16x32_bf16 v[114:117], v[188:191], v[220:223], v[114:117]
	v_mfma_f32_16x16x32_bf16 v[106:109], v[212:215], v[220:223], v[106:109]
	v_mfma_f32_16x16x32_bf16 v[98:101], v[188:191], v[228:231], v[98:101]
	v_mfma_f32_16x16x32_bf16 v[90:93], v[212:215], v[228:231], v[90:93]
	v_mfma_f32_16x16x32_bf16 v[82:85], v[188:191], v[236:239], v[82:85]
	v_mfma_f32_16x16x32_bf16 v[74:77], v[212:215], v[236:239], v[74:77]
	v_mfma_f32_16x16x32_bf16 v[70:73], v[188:191], v[244:247], v[70:73]
	v_mfma_f32_16x16x32_bf16 v[66:69], v[212:215], v[244:247], v[66:69]
	s_setprio 0
	s_barrier
	s_add_i32 s37, s37, s45
	v_lshl_add_u64 v[152:153], s[6:7], 0, v[136:137]
	s_mov_b32 m0, s37
	ds_read_b128 v[216:219], v161 offset:16384
	ds_read_b128 v[220:223], v161 offset:17408
	ds_read_b128 v[224:227], v161 offset:18432
	ds_read_b128 v[228:231], v161 offset:19456
	ds_read_b128 v[232:235], v161 offset:20480
	ds_read_b128 v[236:239], v161 offset:21504
	ds_read_b128 v[240:243], v161 offset:22528
	ds_read_b128 v[244:247], v161 offset:23552
	global_load_lds_dwordx4 v[152:153], off
	s_add_i32 m0, s37, 0x2000
	s_add_u32 s38, s6, 0x40000
	v_lshl_add_u64 v[206:207], s[6:7], 0, v[132:133]
	s_addc_u32 s39, s7, 0
	s_add_i32 s37, s73, s45
	global_load_lds_dwordx4 v[206:207], off
	v_lshl_add_u64 v[248:249], s[38:39], 0, v[136:137]
	s_mov_b32 m0, s37
	v_lshl_add_u64 v[250:251], s[26:27], 0, v[134:135]
	global_load_lds_dwordx4 v[248:249], off
	v_lshl_add_u64 v[248:249], s[38:39], 0, v[132:133]
	s_add_i32 m0, s37, 0x2000
	s_nop 0
	global_load_lds_dwordx4 v[248:249], off
	v_lshl_add_u64 v[248:249], s[26:27], 0, v[138:139]
	s_mov_b32 m0, s57
	s_nop 0
	global_load_lds_dwordx4 v[248:249], off
	s_mov_b32 m0, s70
	s_nop 0
	global_load_lds_dwordx4 v[250:251], off
	s_waitcnt vmcnt(8)
	s_waitcnt lgkmcnt(0)
	s_barrier
	s_setprio 1
	s_waitcnt lgkmcnt(0)
	v_mfma_f32_16x16x32_bf16 v[62:65], v[144:147], v[216:219], v[62:65]
	v_mfma_f32_16x16x32_bf16 v[58:61], v[164:167], v[216:219], v[58:61]
	v_mfma_f32_16x16x32_bf16 v[54:57], v[144:147], v[224:227], v[54:57]
	v_mfma_f32_16x16x32_bf16 v[46:49], v[164:167], v[224:227], v[46:49]
	v_mfma_f32_16x16x32_bf16 v[38:41], v[144:147], v[232:235], v[38:41]
	v_mfma_f32_16x16x32_bf16 v[30:33], v[164:167], v[232:235], v[30:33]
	v_mfma_f32_16x16x32_bf16 v[22:25], v[144:147], v[240:243], v[22:25]
	v_mfma_f32_16x16x32_bf16 v[14:17], v[164:167], v[240:243], v[14:17]
	v_mfma_f32_16x16x32_bf16 v[62:65], v[148:151], v[220:223], v[62:65]
	v_mfma_f32_16x16x32_bf16 v[58:61], v[168:171], v[220:223], v[58:61]
	v_mfma_f32_16x16x32_bf16 v[54:57], v[148:151], v[228:231], v[54:57]
	v_mfma_f32_16x16x32_bf16 v[46:49], v[168:171], v[228:231], v[46:49]
	v_mfma_f32_16x16x32_bf16 v[38:41], v[148:151], v[236:239], v[38:41]
	v_mfma_f32_16x16x32_bf16 v[30:33], v[168:171], v[236:239], v[30:33]
	v_mfma_f32_16x16x32_bf16 v[22:25], v[148:151], v[244:247], v[22:25]
	v_mfma_f32_16x16x32_bf16 v[14:17], v[168:171], v[244:247], v[14:17]
	s_setprio 0
	s_setprio 1
	v_mfma_f32_16x16x32_bf16 v[50:53], v[172:175], v[216:219], v[50:53]
	v_mfma_f32_16x16x32_bf16 v[42:45], v[192:195], v[216:219], v[42:45]
	v_mfma_f32_16x16x32_bf16 v[34:37], v[172:175], v[224:227], v[34:37]
	v_mfma_f32_16x16x32_bf16 v[26:29], v[192:195], v[224:227], v[26:29]
	v_mfma_f32_16x16x32_bf16 v[18:21], v[172:175], v[232:235], v[18:21]
	v_mfma_f32_16x16x32_bf16 v[10:13], v[192:195], v[232:235], v[10:13]
	v_mfma_f32_16x16x32_bf16 v[6:9], v[172:175], v[240:243], v[6:9]
	v_mfma_f32_16x16x32_bf16 v[2:5], v[192:195], v[240:243], v[2:5]
	v_mfma_f32_16x16x32_bf16 v[50:53], v[188:191], v[220:223], v[50:53]
	v_mfma_f32_16x16x32_bf16 v[42:45], v[212:215], v[220:223], v[42:45]
	v_mfma_f32_16x16x32_bf16 v[34:37], v[188:191], v[228:231], v[34:37]
	v_mfma_f32_16x16x32_bf16 v[26:29], v[212:215], v[228:231], v[26:29]
	v_mfma_f32_16x16x32_bf16 v[18:21], v[188:191], v[236:239], v[18:21]
	v_mfma_f32_16x16x32_bf16 v[10:13], v[212:215], v[236:239], v[10:13]
	v_mfma_f32_16x16x32_bf16 v[6:9], v[188:191], v[244:247], v[6:9]
	v_mfma_f32_16x16x32_bf16 v[2:5], v[212:215], v[244:247], v[2:5]
	s_setprio 0
	s_barrier
	s_add_i32 s37, 0, 0x18000
	v_add_u32_e32 v163, s37, v156
	s_add_i32 s38, 0, 0x1c000
	ds_read_b128 v[144:147], v163
	ds_read_b128 v[148:151], v163 offset:1024
	ds_read_b128 v[164:167], v163 offset:2048
	ds_read_b128 v[168:171], v163 offset:3072
	v_add_u32_e32 v163, s38, v156
	ds_read_b128 v[172:175], v163
	ds_read_b128 v[188:191], v163 offset:1024
	ds_read_b128 v[192:195], v163 offset:2048
	ds_read_b128 v[212:215], v163 offset:3072
	s_add_u32 s26, s26, 0x40000
	s_addc_u32 s27, s27, 0
	s_mov_b32 m0, s71
	v_lshl_add_u64 v[252:253], s[26:27], 0, v[138:139]
	ds_read_b128 v[216:219], v161 offset:32768
	ds_read_b128 v[220:223], v161 offset:33792
	ds_read_b128 v[224:227], v161 offset:34816
	ds_read_b128 v[228:231], v161 offset:35840
	ds_read_b128 v[232:235], v161 offset:36864
	ds_read_b128 v[236:239], v161 offset:37888
	ds_read_b128 v[240:243], v161 offset:38912
	ds_read_b128 v[244:247], v161 offset:39936
	global_load_lds_dwordx4 v[252:253], off
	v_lshl_add_u64 v[252:253], s[26:27], 0, v[134:135]
	s_mov_b32 m0, s74
	s_nop 0
	global_load_lds_dwordx4 v[252:253], off
	s_waitcnt vmcnt(8)
	s_waitcnt lgkmcnt(0)
	s_barrier
	s_setprio 1
	s_waitcnt lgkmcnt(0)
	v_mfma_f32_16x16x32_bf16 v[126:129], v[144:147], v[216:219], v[126:129]
	v_mfma_f32_16x16x32_bf16 v[122:125], v[164:167], v[216:219], v[122:125]
	v_mfma_f32_16x16x32_bf16 v[118:121], v[144:147], v[224:227], v[118:121]
	v_mfma_f32_16x16x32_bf16 v[110:113], v[164:167], v[224:227], v[110:113]
	v_mfma_f32_16x16x32_bf16 v[102:105], v[144:147], v[232:235], v[102:105]
	v_mfma_f32_16x16x32_bf16 v[94:97], v[164:167], v[232:235], v[94:97]
	v_mfma_f32_16x16x32_bf16 v[86:89], v[144:147], v[240:243], v[86:89]
	v_mfma_f32_16x16x32_bf16 v[78:81], v[164:167], v[240:243], v[78:81]
	v_mfma_f32_16x16x32_bf16 v[126:129], v[148:151], v[220:223], v[126:129]
	v_mfma_f32_16x16x32_bf16 v[122:125], v[168:171], v[220:223], v[122:125]
	v_mfma_f32_16x16x32_bf16 v[118:121], v[148:151], v[228:231], v[118:121]
	v_mfma_f32_16x16x32_bf16 v[110:113], v[168:171], v[228:231], v[110:113]
	v_mfma_f32_16x16x32_bf16 v[102:105], v[148:151], v[236:239], v[102:105]
	v_mfma_f32_16x16x32_bf16 v[94:97], v[168:171], v[236:239], v[94:97]
	v_mfma_f32_16x16x32_bf16 v[86:89], v[148:151], v[244:247], v[86:89]
	v_mfma_f32_16x16x32_bf16 v[78:81], v[168:171], v[244:247], v[78:81]
	s_setprio 0
	s_setprio 1
	v_mfma_f32_16x16x32_bf16 v[114:117], v[172:175], v[216:219], v[114:117]
	v_mfma_f32_16x16x32_bf16 v[106:109], v[192:195], v[216:219], v[106:109]
	v_mfma_f32_16x16x32_bf16 v[98:101], v[172:175], v[224:227], v[98:101]
	v_mfma_f32_16x16x32_bf16 v[90:93], v[192:195], v[224:227], v[90:93]
	v_mfma_f32_16x16x32_bf16 v[82:85], v[172:175], v[232:235], v[82:85]
	v_mfma_f32_16x16x32_bf16 v[74:77], v[192:195], v[232:235], v[74:77]
	v_mfma_f32_16x16x32_bf16 v[70:73], v[172:175], v[240:243], v[70:73]
	v_mfma_f32_16x16x32_bf16 v[66:69], v[192:195], v[240:243], v[66:69]
	v_mfma_f32_16x16x32_bf16 v[114:117], v[188:191], v[220:223], v[114:117]
	v_mfma_f32_16x16x32_bf16 v[106:109], v[212:215], v[220:223], v[106:109]
	v_mfma_f32_16x16x32_bf16 v[98:101], v[188:191], v[228:231], v[98:101]
	v_mfma_f32_16x16x32_bf16 v[90:93], v[212:215], v[228:231], v[90:93]
	v_mfma_f32_16x16x32_bf16 v[82:85], v[188:191], v[236:239], v[82:85]
	v_mfma_f32_16x16x32_bf16 v[74:77], v[212:215], v[236:239], v[74:77]
	v_mfma_f32_16x16x32_bf16 v[70:73], v[188:191], v[244:247], v[70:73]
	v_mfma_f32_16x16x32_bf16 v[66:69], v[212:215], v[244:247], v[66:69]
	s_setprio 0
	s_barrier
	s_add_i32 s26, s37, s45
	v_lshl_add_u64 v[152:153], v[152:153], 0, s[68:69]
	s_mov_b32 m0, s26
	ds_read_b128 v[216:219], v161 offset:49152
	ds_read_b128 v[220:223], v161 offset:50176
	ds_read_b128 v[224:227], v161 offset:51200
	ds_read_b128 v[228:231], v161 offset:52224
	ds_read_b128 v[232:235], v161 offset:53248
	ds_read_b128 v[236:239], v161 offset:54272
	ds_read_b128 v[240:243], v161 offset:55296
	ds_read_b128 v[244:247], v161 offset:56320
	global_load_lds_dwordx4 v[152:153], off
	s_add_i32 m0, s26, 0x2000
	s_add_u32 s6, s6, 0x40080
	v_lshl_add_u64 v[152:153], v[206:207], 0, s[68:69]
	s_addc_u32 s7, s7, 0
	s_add_i32 s26, s38, s45
	global_load_lds_dwordx4 v[152:153], off
	v_lshl_add_u64 v[152:153], s[6:7], 0, v[136:137]
	s_mov_b32 m0, s26
	s_nop 0
	global_load_lds_dwordx4 v[152:153], off
	v_lshl_add_u64 v[152:153], s[6:7], 0, v[132:133]
	s_add_i32 m0, s26, 0x2000
	s_nop 0
	global_load_lds_dwordx4 v[152:153], off
	v_lshl_add_u64 v[152:153], v[248:249], 0, s[68:69]
	s_mov_b32 m0, s85
	s_nop 0
	global_load_lds_dwordx4 v[152:153], off
	v_lshl_add_u64 v[152:153], v[250:251], 0, s[68:69]
	s_mov_b32 m0, s18
	s_nop 0
	global_load_lds_dwordx4 v[152:153], off
	s_waitcnt vmcnt(8)
	s_waitcnt lgkmcnt(0)
	s_barrier
	s_setprio 1
	s_waitcnt lgkmcnt(0)
	v_mfma_f32_16x16x32_bf16 v[62:65], v[144:147], v[216:219], v[62:65]
	v_mfma_f32_16x16x32_bf16 v[58:61], v[164:167], v[216:219], v[58:61]
	v_mfma_f32_16x16x32_bf16 v[54:57], v[144:147], v[224:227], v[54:57]
	v_mfma_f32_16x16x32_bf16 v[46:49], v[164:167], v[224:227], v[46:49]
	v_mfma_f32_16x16x32_bf16 v[38:41], v[144:147], v[232:235], v[38:41]
	v_mfma_f32_16x16x32_bf16 v[30:33], v[164:167], v[232:235], v[30:33]
	v_mfma_f32_16x16x32_bf16 v[22:25], v[144:147], v[240:243], v[22:25]
	v_mfma_f32_16x16x32_bf16 v[14:17], v[164:167], v[240:243], v[14:17]
	v_mfma_f32_16x16x32_bf16 v[62:65], v[148:151], v[220:223], v[62:65]
	v_mfma_f32_16x16x32_bf16 v[58:61], v[168:171], v[220:223], v[58:61]
	v_mfma_f32_16x16x32_bf16 v[54:57], v[148:151], v[228:231], v[54:57]
	v_mfma_f32_16x16x32_bf16 v[46:49], v[168:171], v[228:231], v[46:49]
	v_mfma_f32_16x16x32_bf16 v[38:41], v[148:151], v[236:239], v[38:41]
	v_mfma_f32_16x16x32_bf16 v[30:33], v[168:171], v[236:239], v[30:33]
	v_mfma_f32_16x16x32_bf16 v[22:25], v[148:151], v[244:247], v[22:25]
	v_mfma_f32_16x16x32_bf16 v[14:17], v[168:171], v[244:247], v[14:17]
	s_setprio 0
	s_setprio 1
	v_mfma_f32_16x16x32_bf16 v[50:53], v[172:175], v[216:219], v[50:53]
	v_mfma_f32_16x16x32_bf16 v[42:45], v[192:195], v[216:219], v[42:45]
	v_mfma_f32_16x16x32_bf16 v[34:37], v[172:175], v[224:227], v[34:37]
	v_mfma_f32_16x16x32_bf16 v[26:29], v[192:195], v[224:227], v[26:29]
	v_mfma_f32_16x16x32_bf16 v[18:21], v[172:175], v[232:235], v[18:21]
	v_mfma_f32_16x16x32_bf16 v[10:13], v[192:195], v[232:235], v[10:13]
	v_mfma_f32_16x16x32_bf16 v[6:9], v[172:175], v[240:243], v[6:9]
	v_mfma_f32_16x16x32_bf16 v[2:5], v[192:195], v[240:243], v[2:5]
	v_mfma_f32_16x16x32_bf16 v[50:53], v[188:191], v[220:223], v[50:53]
	v_mfma_f32_16x16x32_bf16 v[42:45], v[212:215], v[220:223], v[42:45]
	v_mfma_f32_16x16x32_bf16 v[34:37], v[188:191], v[228:231], v[34:37]
	v_mfma_f32_16x16x32_bf16 v[26:29], v[212:215], v[228:231], v[26:29]
	v_mfma_f32_16x16x32_bf16 v[18:21], v[188:191], v[236:239], v[18:21]
	v_mfma_f32_16x16x32_bf16 v[10:13], v[212:215], v[236:239], v[10:13]
	v_mfma_f32_16x16x32_bf16 v[6:9], v[188:191], v[244:247], v[6:9]
	v_mfma_f32_16x16x32_bf16 v[2:5], v[212:215], v[244:247], v[2:5]
	s_add_i32 s36, s36, 2
	s_add_u32 s24, s24, 0x100
	s_addc_u32 s25, s25, 0
	s_add_u32 s34, s34, 0x100
	s_addc_u32 s35, s35, 0
	s_setprio 0
	s_barrier
	s_cmp_gt_u32 s36, 13
	s_cbranch_scc0 .LBB0_287
	s_and_b64 vcc, exec, s[62:63]
	s_cbranch_vccz .LBB0_290
	s_barrier

.LBB0_319:
	s_add_u32 s26, s24, 0xfffc0080
	s_addc_u32 s27, s25, -1
	s_add_i32 s39, 0, 0x10000
	s_cmp_eq_u32 s38, 12
	s_cselect_b32 s29, s10, s27
	s_cselect_b32 s28, s31, s26
	v_add_u32_e32 v143, s39, v153
	s_cselect_b32 s27, s34, s37
	s_cselect_b32 s26, s35, s36
	s_add_i32 s59, 0, 0x14000
	ds_read_b128 v[148:151], v143
	ds_read_b128 v[158:161], v143 offset:1024
	ds_read_b128 v[162:165], v143 offset:2048
	ds_read_b128 v[166:169], v143 offset:3072
	v_add_u32_e32 v143, s59, v153
	ds_read_b128 v[170:173], v143
	ds_read_b128 v[188:191], v143 offset:1024
	ds_read_b128 v[192:195], v143 offset:2048
	ds_read_b128 v[212:215], v143 offset:3072
	v_lshl_add_u64 v[174:175], s[24:25], 0, v[138:139]
	s_add_i32 m0, s57, 0xc000
	ds_read_b128 v[216:219], v156
	ds_read_b128 v[220:223], v156 offset:1024
	ds_read_b128 v[224:227], v156 offset:2048
	ds_read_b128 v[228:231], v156 offset:3072
	ds_read_b128 v[232:235], v156 offset:4096
	ds_read_b128 v[236:239], v156 offset:5120
	ds_read_b128 v[240:243], v156 offset:6144
	ds_read_b128 v[244:247], v156 offset:7168
	global_load_lds_dwordx4 v[174:175], off
	v_lshl_add_u64 v[174:175], s[24:25], 0, v[140:141]
	s_add_i32 m0, s57, 0xe000
	s_nop 0
	global_load_lds_dwordx4 v[174:175], off
	s_waitcnt vmcnt(8)
	s_waitcnt lgkmcnt(0)
	s_barrier
	s_setprio 1
	s_waitcnt lgkmcnt(0)
	v_mfma_f32_16x16x32_bf16 v[126:129], v[148:151], v[216:219], v[126:129]
	v_mfma_f32_16x16x32_bf16 v[122:125], v[162:165], v[216:219], v[122:125]
	v_mfma_f32_16x16x32_bf16 v[118:121], v[148:151], v[224:227], v[118:121]
	v_mfma_f32_16x16x32_bf16 v[110:113], v[162:165], v[224:227], v[110:113]
	v_mfma_f32_16x16x32_bf16 v[102:105], v[148:151], v[232:235], v[102:105]
	v_mfma_f32_16x16x32_bf16 v[94:97], v[162:165], v[232:235], v[94:97]
	v_mfma_f32_16x16x32_bf16 v[86:89], v[148:151], v[240:243], v[86:89]
	v_mfma_f32_16x16x32_bf16 v[78:81], v[162:165], v[240:243], v[78:81]
	v_mfma_f32_16x16x32_bf16 v[126:129], v[158:161], v[220:223], v[126:129]
	v_mfma_f32_16x16x32_bf16 v[122:125], v[166:169], v[220:223], v[122:125]
	v_mfma_f32_16x16x32_bf16 v[118:121], v[158:161], v[228:231], v[118:121]
	v_mfma_f32_16x16x32_bf16 v[110:113], v[166:169], v[228:231], v[110:113]
	v_mfma_f32_16x16x32_bf16 v[102:105], v[158:161], v[236:239], v[102:105]
	v_mfma_f32_16x16x32_bf16 v[94:97], v[166:169], v[236:239], v[94:97]
	v_mfma_f32_16x16x32_bf16 v[86:89], v[158:161], v[244:247], v[86:89]
	v_mfma_f32_16x16x32_bf16 v[78:81], v[166:169], v[244:247], v[78:81]
	s_setprio 0
	s_setprio 1
	v_mfma_f32_16x16x32_bf16 v[114:117], v[170:173], v[216:219], v[114:117]
	v_mfma_f32_16x16x32_bf16 v[106:109], v[192:195], v[216:219], v[106:109]
	v_mfma_f32_16x16x32_bf16 v[98:101], v[170:173], v[224:227], v[98:101]
	v_mfma_f32_16x16x32_bf16 v[90:93], v[192:195], v[224:227], v[90:93]
	v_mfma_f32_16x16x32_bf16 v[82:85], v[170:173], v[232:235], v[82:85]
	v_mfma_f32_16x16x32_bf16 v[74:77], v[192:195], v[232:235], v[74:77]
	v_mfma_f32_16x16x32_bf16 v[70:73], v[170:173], v[240:243], v[70:73]
	v_mfma_f32_16x16x32_bf16 v[66:69], v[192:195], v[240:243], v[66:69]
	v_mfma_f32_16x16x32_bf16 v[114:117], v[188:191], v[220:223], v[114:117]
	v_mfma_f32_16x16x32_bf16 v[106:109], v[212:215], v[220:223], v[106:109]
	v_mfma_f32_16x16x32_bf16 v[98:101], v[188:191], v[228:231], v[98:101]
	v_mfma_f32_16x16x32_bf16 v[90:93], v[212:215], v[228:231], v[90:93]
	v_mfma_f32_16x16x32_bf16 v[82:85], v[188:191], v[236:239], v[82:85]
	v_mfma_f32_16x16x32_bf16 v[74:77], v[212:215], v[236:239], v[74:77]
	v_mfma_f32_16x16x32_bf16 v[70:73], v[188:191], v[244:247], v[70:73]
	v_mfma_f32_16x16x32_bf16 v[66:69], v[212:215], v[244:247], v[66:69]
	s_setprio 0
	s_barrier
	s_add_i32 s39, s39, s45
	v_lshl_add_u64 v[174:175], s[26:27], 0, v[134:135]
	s_mov_b32 m0, s39
	ds_read_b128 v[216:219], v156 offset:16384
	ds_read_b128 v[220:223], v156 offset:17408
	ds_read_b128 v[224:227], v156 offset:18432
	ds_read_b128 v[228:231], v156 offset:19456
	ds_read_b128 v[232:235], v156 offset:20480
	ds_read_b128 v[236:239], v156 offset:21504
	ds_read_b128 v[240:243], v156 offset:22528
	ds_read_b128 v[244:247], v156 offset:23552
	global_load_lds_dwordx4 v[174:175], off
	s_add_i32 m0, s39, 0x2000
	s_add_u32 s94, s26, 0x40000
	v_lshl_add_u64 v[248:249], s[26:27], 0, v[130:131]
	s_addc_u32 s95, s27, 0
	s_add_i32 s39, s59, s45
	global_load_lds_dwordx4 v[248:249], off
	v_lshl_add_u64 v[250:251], s[94:95], 0, v[134:135]
	s_mov_b32 m0, s39
	v_lshl_add_u64 v[252:253], s[28:29], 0, v[132:133]
	global_load_lds_dwordx4 v[250:251], off
	v_lshl_add_u64 v[250:251], s[94:95], 0, v[130:131]
	s_add_i32 m0, s39, 0x2000
	s_nop 0
	global_load_lds_dwordx4 v[250:251], off
	v_lshl_add_u64 v[250:251], s[28:29], 0, v[136:137]
	s_mov_b32 m0, s57
	s_nop 0
	global_load_lds_dwordx4 v[250:251], off
	s_mov_b32 m0, s70
	s_nop 0
	global_load_lds_dwordx4 v[252:253], off
	s_waitcnt vmcnt(8)
	s_waitcnt lgkmcnt(0)
	s_barrier
	s_setprio 1
	s_waitcnt lgkmcnt(0)
	v_mfma_f32_16x16x32_bf16 v[62:65], v[148:151], v[216:219], v[62:65]
	v_mfma_f32_16x16x32_bf16 v[58:61], v[162:165], v[216:219], v[58:61]
	v_mfma_f32_16x16x32_bf16 v[54:57], v[148:151], v[224:227], v[54:57]
	v_mfma_f32_16x16x32_bf16 v[46:49], v[162:165], v[224:227], v[46:49]
	v_mfma_f32_16x16x32_bf16 v[38:41], v[148:151], v[232:235], v[38:41]
	v_mfma_f32_16x16x32_bf16 v[30:33], v[162:165], v[232:235], v[30:33]
	v_mfma_f32_16x16x32_bf16 v[22:25], v[148:151], v[240:243], v[22:25]
	v_mfma_f32_16x16x32_bf16 v[14:17], v[162:165], v[240:243], v[14:17]
	v_mfma_f32_16x16x32_bf16 v[62:65], v[158:161], v[220:223], v[62:65]
	v_mfma_f32_16x16x32_bf16 v[58:61], v[166:169], v[220:223], v[58:61]
	v_mfma_f32_16x16x32_bf16 v[54:57], v[158:161], v[228:231], v[54:57]
	v_mfma_f32_16x16x32_bf16 v[46:49], v[166:169], v[228:231], v[46:49]
	v_mfma_f32_16x16x32_bf16 v[38:41], v[158:161], v[236:239], v[38:41]
	v_mfma_f32_16x16x32_bf16 v[30:33], v[166:169], v[236:239], v[30:33]
	v_mfma_f32_16x16x32_bf16 v[22:25], v[158:161], v[244:247], v[22:25]
	v_mfma_f32_16x16x32_bf16 v[14:17], v[166:169], v[244:247], v[14:17]
	s_setprio 0
	s_setprio 1
	v_mfma_f32_16x16x32_bf16 v[50:53], v[170:173], v[216:219], v[50:53]
	v_mfma_f32_16x16x32_bf16 v[42:45], v[192:195], v[216:219], v[42:45]
	v_mfma_f32_16x16x32_bf16 v[34:37], v[170:173], v[224:227], v[34:37]
	v_mfma_f32_16x16x32_bf16 v[26:29], v[192:195], v[224:227], v[26:29]
	v_mfma_f32_16x16x32_bf16 v[18:21], v[170:173], v[232:235], v[18:21]
	v_mfma_f32_16x16x32_bf16 v[10:13], v[192:195], v[232:235], v[10:13]
	v_mfma_f32_16x16x32_bf16 v[6:9], v[170:173], v[240:243], v[6:9]
	v_mfma_f32_16x16x32_bf16 v[2:5], v[192:195], v[240:243], v[2:5]
	v_mfma_f32_16x16x32_bf16 v[50:53], v[188:191], v[220:223], v[50:53]
	v_mfma_f32_16x16x32_bf16 v[42:45], v[212:215], v[220:223], v[42:45]
	v_mfma_f32_16x16x32_bf16 v[34:37], v[188:191], v[228:231], v[34:37]
	v_mfma_f32_16x16x32_bf16 v[26:29], v[212:215], v[228:231], v[26:29]
	v_mfma_f32_16x16x32_bf16 v[18:21], v[188:191], v[236:239], v[18:21]
	v_mfma_f32_16x16x32_bf16 v[10:13], v[212:215], v[236:239], v[10:13]
	v_mfma_f32_16x16x32_bf16 v[6:9], v[188:191], v[244:247], v[6:9]
	v_mfma_f32_16x16x32_bf16 v[2:5], v[212:215], v[244:247], v[2:5]
	s_setprio 0
	s_barrier
	s_add_i32 s39, 0, 0x18000
	v_add_u32_e32 v143, s39, v153
	s_add_i32 s59, 0, 0x1c000
	ds_read_b128 v[148:151], v143
	ds_read_b128 v[158:161], v143 offset:1024
	ds_read_b128 v[162:165], v143 offset:2048
	ds_read_b128 v[166:169], v143 offset:3072
	v_add_u32_e32 v143, s59, v153
	ds_read_b128 v[170:173], v143
	ds_read_b128 v[188:191], v143 offset:1024
	ds_read_b128 v[192:195], v143 offset:2048
	ds_read_b128 v[212:215], v143 offset:3072
	s_add_u32 s28, s28, 0x40000
	s_addc_u32 s29, s29, 0
	s_mov_b32 m0, s18
	v_lshl_add_u64 v[206:207], s[28:29], 0, v[136:137]
	ds_read_b128 v[216:219], v156 offset:32768
	ds_read_b128 v[220:223], v156 offset:33792
	ds_read_b128 v[224:227], v156 offset:34816
	ds_read_b128 v[228:231], v156 offset:35840
	ds_read_b128 v[232:235], v156 offset:36864
	ds_read_b128 v[236:239], v156 offset:37888
	ds_read_b128 v[240:243], v156 offset:38912
	ds_read_b128 v[244:247], v156 offset:39936
	global_load_lds_dwordx4 v[206:207], off
	v_lshl_add_u64 v[206:207], s[28:29], 0, v[132:133]
	s_mov_b32 m0, s71
	s_nop 0
	global_load_lds_dwordx4 v[206:207], off
	s_waitcnt vmcnt(8)
	s_waitcnt lgkmcnt(0)
	s_barrier
	s_setprio 1
	s_waitcnt lgkmcnt(0)
	v_mfma_f32_16x16x32_bf16 v[126:129], v[148:151], v[216:219], v[126:129]
	v_mfma_f32_16x16x32_bf16 v[122:125], v[162:165], v[216:219], v[122:125]
	v_mfma_f32_16x16x32_bf16 v[118:121], v[148:151], v[224:227], v[118:121]
	v_mfma_f32_16x16x32_bf16 v[110:113], v[162:165], v[224:227], v[110:113]
	v_mfma_f32_16x16x32_bf16 v[102:105], v[148:151], v[232:235], v[102:105]
	v_mfma_f32_16x16x32_bf16 v[94:97], v[162:165], v[232:235], v[94:97]
	v_mfma_f32_16x16x32_bf16 v[86:89], v[148:151], v[240:243], v[86:89]
	v_mfma_f32_16x16x32_bf16 v[78:81], v[162:165], v[240:243], v[78:81]
	v_mfma_f32_16x16x32_bf16 v[126:129], v[158:161], v[220:223], v[126:129]
	v_mfma_f32_16x16x32_bf16 v[122:125], v[166:169], v[220:223], v[122:125]
	v_mfma_f32_16x16x32_bf16 v[118:121], v[158:161], v[228:231], v[118:121]
	v_mfma_f32_16x16x32_bf16 v[110:113], v[166:169], v[228:231], v[110:113]
	v_mfma_f32_16x16x32_bf16 v[102:105], v[158:161], v[236:239], v[102:105]
	v_mfma_f32_16x16x32_bf16 v[94:97], v[166:169], v[236:239], v[94:97]
	v_mfma_f32_16x16x32_bf16 v[86:89], v[158:161], v[244:247], v[86:89]
	v_mfma_f32_16x16x32_bf16 v[78:81], v[166:169], v[244:247], v[78:81]
	s_setprio 0
	s_setprio 1
	v_mfma_f32_16x16x32_bf16 v[114:117], v[170:173], v[216:219], v[114:117]
	v_mfma_f32_16x16x32_bf16 v[106:109], v[192:195], v[216:219], v[106:109]
	v_mfma_f32_16x16x32_bf16 v[98:101], v[170:173], v[224:227], v[98:101]
	v_mfma_f32_16x16x32_bf16 v[90:93], v[192:195], v[224:227], v[90:93]
	v_mfma_f32_16x16x32_bf16 v[82:85], v[170:173], v[232:235], v[82:85]
	v_mfma_f32_16x16x32_bf16 v[74:77], v[192:195], v[232:235], v[74:77]
	v_mfma_f32_16x16x32_bf16 v[70:73], v[170:173], v[240:243], v[70:73]
	v_mfma_f32_16x16x32_bf16 v[66:69], v[192:195], v[240:243], v[66:69]
	v_mfma_f32_16x16x32_bf16 v[114:117], v[188:191], v[220:223], v[114:117]
	v_mfma_f32_16x16x32_bf16 v[106:109], v[212:215], v[220:223], v[106:109]
	v_mfma_f32_16x16x32_bf16 v[98:101], v[188:191], v[228:231], v[98:101]
	v_mfma_f32_16x16x32_bf16 v[90:93], v[212:215], v[228:231], v[90:93]
	v_mfma_f32_16x16x32_bf16 v[82:85], v[188:191], v[236:239], v[82:85]
	v_mfma_f32_16x16x32_bf16 v[74:77], v[212:215], v[236:239], v[74:77]
	v_mfma_f32_16x16x32_bf16 v[70:73], v[188:191], v[244:247], v[70:73]
	v_mfma_f32_16x16x32_bf16 v[66:69], v[212:215], v[244:247], v[66:69]
	s_setprio 0
	s_barrier
	s_add_i32 s28, s39, s45
	v_lshl_add_u64 v[174:175], v[174:175], 0, s[68:69]
	s_mov_b32 m0, s28
	ds_read_b128 v[216:219], v156 offset:49152
	ds_read_b128 v[220:223], v156 offset:50176
	ds_read_b128 v[224:227], v156 offset:51200
	ds_read_b128 v[228:231], v156 offset:52224
	ds_read_b128 v[232:235], v156 offset:53248
	ds_read_b128 v[236:239], v156 offset:54272
	ds_read_b128 v[240:243], v156 offset:55296
	ds_read_b128 v[244:247], v156 offset:56320
	global_load_lds_dwordx4 v[174:175], off
	s_add_i32 m0, s28, 0x2000
	s_add_u32 s26, s26, 0x40080
	v_lshl_add_u64 v[174:175], v[248:249], 0, s[68:69]
	s_addc_u32 s27, s27, 0
	s_add_i32 s28, s59, s45
	global_load_lds_dwordx4 v[174:175], off
	v_lshl_add_u64 v[174:175], s[26:27], 0, v[134:135]
	s_mov_b32 m0, s28
	s_nop 0
	global_load_lds_dwordx4 v[174:175], off
	v_lshl_add_u64 v[174:175], s[26:27], 0, v[130:131]
	s_add_i32 m0, s28, 0x2000
	s_nop 0
	global_load_lds_dwordx4 v[174:175], off
	v_lshl_add_u64 v[174:175], v[250:251], 0, s[68:69]
	s_mov_b32 m0, s85
	s_nop 0
	global_load_lds_dwordx4 v[174:175], off
	v_lshl_add_u64 v[174:175], v[252:253], 0, s[68:69]
	s_mov_b32 m0, s8
	s_nop 0
	global_load_lds_dwordx4 v[174:175], off
	s_waitcnt vmcnt(8)
	s_waitcnt lgkmcnt(0)
	s_barrier
	s_setprio 1
	s_waitcnt lgkmcnt(0)
	v_mfma_f32_16x16x32_bf16 v[62:65], v[148:151], v[216:219], v[62:65]
	v_mfma_f32_16x16x32_bf16 v[58:61], v[162:165], v[216:219], v[58:61]
	v_mfma_f32_16x16x32_bf16 v[54:57], v[148:151], v[224:227], v[54:57]
	v_mfma_f32_16x16x32_bf16 v[46:49], v[162:165], v[224:227], v[46:49]
	v_mfma_f32_16x16x32_bf16 v[38:41], v[148:151], v[232:235], v[38:41]
	v_mfma_f32_16x16x32_bf16 v[30:33], v[162:165], v[232:235], v[30:33]
	v_mfma_f32_16x16x32_bf16 v[22:25], v[148:151], v[240:243], v[22:25]
	v_mfma_f32_16x16x32_bf16 v[14:17], v[162:165], v[240:243], v[14:17]
	v_mfma_f32_16x16x32_bf16 v[62:65], v[158:161], v[220:223], v[62:65]
	v_mfma_f32_16x16x32_bf16 v[58:61], v[166:169], v[220:223], v[58:61]
	v_mfma_f32_16x16x32_bf16 v[54:57], v[158:161], v[228:231], v[54:57]
	v_mfma_f32_16x16x32_bf16 v[46:49], v[166:169], v[228:231], v[46:49]
	v_mfma_f32_16x16x32_bf16 v[38:41], v[158:161], v[236:239], v[38:41]
	v_mfma_f32_16x16x32_bf16 v[30:33], v[166:169], v[236:239], v[30:33]
	v_mfma_f32_16x16x32_bf16 v[22:25], v[158:161], v[244:247], v[22:25]
	v_mfma_f32_16x16x32_bf16 v[14:17], v[166:169], v[244:247], v[14:17]
	s_setprio 0
	s_setprio 1
	v_mfma_f32_16x16x32_bf16 v[50:53], v[170:173], v[216:219], v[50:53]
	v_mfma_f32_16x16x32_bf16 v[42:45], v[192:195], v[216:219], v[42:45]
	v_mfma_f32_16x16x32_bf16 v[34:37], v[170:173], v[224:227], v[34:37]
	v_mfma_f32_16x16x32_bf16 v[26:29], v[192:195], v[224:227], v[26:29]
	v_mfma_f32_16x16x32_bf16 v[18:21], v[170:173], v[232:235], v[18:21]
	v_mfma_f32_16x16x32_bf16 v[10:13], v[192:195], v[232:235], v[10:13]
	v_mfma_f32_16x16x32_bf16 v[6:9], v[170:173], v[240:243], v[6:9]
	v_mfma_f32_16x16x32_bf16 v[2:5], v[192:195], v[240:243], v[2:5]
	v_mfma_f32_16x16x32_bf16 v[50:53], v[188:191], v[220:223], v[50:53]
	v_mfma_f32_16x16x32_bf16 v[42:45], v[212:215], v[220:223], v[42:45]
	v_mfma_f32_16x16x32_bf16 v[34:37], v[188:191], v[228:231], v[34:37]
	v_mfma_f32_16x16x32_bf16 v[26:29], v[212:215], v[228:231], v[26:29]
	v_mfma_f32_16x16x32_bf16 v[18:21], v[188:191], v[236:239], v[18:21]
	v_mfma_f32_16x16x32_bf16 v[10:13], v[212:215], v[236:239], v[10:13]
	v_mfma_f32_16x16x32_bf16 v[6:9], v[188:191], v[244:247], v[6:9]
	v_mfma_f32_16x16x32_bf16 v[2:5], v[212:215], v[244:247], v[2:5]
	s_add_i32 s38, s38, 2
	s_add_u32 s24, s24, 0x100
	s_addc_u32 s25, s25, 0
	s_add_u32 s36, s36, 0x100
	s_addc_u32 s37, s37, 0
	s_setprio 0
	s_barrier
	s_cmp_gt_u32 s38, 13
	s_cbranch_scc0 .LBB0_319
	s_and_b64 vcc, exec, s[62:63]
	s_cbranch_vccz .LBB0_322
	s_barrier

.LBB0_743:
	s_add_i32 s70, s26, 2
	s_add_u32 s71, s24, 0x80
	s_addc_u32 s27, s25, 0
	s_add_i32 s73, 0, 0x10000
	s_cmp_eq_u32 s41, s26
	s_cselect_b32 s27, s28, s27
	s_cselect_b32 s26, s29, s71
	s_cselect_b32 s75, s45, s63
	s_cselect_b32 s74, s51, s57
	s_add_i32 s71, 0, 0x14000
	v_add_u32_e32 v156, s73, v141
	v_add_u32_e32 v172, s71, v141
	ds_read_b128 v[144:147], v156
	ds_read_b128 v[148:151], v156 offset:1024
	ds_read_b128 v[152:155], v156 offset:2048
	ds_read_b128 v[156:159], v156 offset:3072
	ds_read_b128 v[160:163], v172
	ds_read_b128 v[164:167], v172 offset:1024
	ds_read_b128 v[168:171], v172 offset:2048
	ds_read_b128 v[172:175], v172 offset:3072
	v_lshl_add_u64 v[206:207], s[24:25], 0, v[136:137]
	s_add_i32 m0, s34, 0xc000
	ds_read_b128 v[188:191], v143
	ds_read_b128 v[192:195], v143 offset:1024
	ds_read_b128 v[212:215], v143 offset:2048
	ds_read_b128 v[216:219], v143 offset:3072
	ds_read_b128 v[220:223], v143 offset:4096
	ds_read_b128 v[224:227], v143 offset:5120
	ds_read_b128 v[228:231], v143 offset:6144
	ds_read_b128 v[232:235], v143 offset:7168
	global_load_lds_dwordx4 v[206:207], off
	v_lshl_add_u64 v[206:207], s[24:25], 0, v[138:139]
	s_add_i32 m0, s34, 0xe000
	s_nop 0
	global_load_lds_dwordx4 v[206:207], off
	s_waitcnt vmcnt(8)
	s_waitcnt lgkmcnt(0)
	s_barrier
	s_setprio 1
	s_waitcnt lgkmcnt(0)
	v_mfma_f32_16x16x32_bf16 v[126:129], v[144:147], v[188:191], v[126:129]
	v_mfma_f32_16x16x32_bf16 v[122:125], v[152:155], v[188:191], v[122:125]
	v_mfma_f32_16x16x32_bf16 v[118:121], v[144:147], v[212:215], v[118:121]
	v_mfma_f32_16x16x32_bf16 v[114:117], v[152:155], v[212:215], v[114:117]
	v_mfma_f32_16x16x32_bf16 v[102:105], v[144:147], v[220:223], v[102:105]
	v_mfma_f32_16x16x32_bf16 v[98:101], v[152:155], v[220:223], v[98:101]
	v_mfma_f32_16x16x32_bf16 v[86:89], v[144:147], v[228:231], v[86:89]
	v_mfma_f32_16x16x32_bf16 v[82:85], v[152:155], v[228:231], v[82:85]
	v_mfma_f32_16x16x32_bf16 v[126:129], v[148:151], v[192:195], v[126:129]
	v_mfma_f32_16x16x32_bf16 v[122:125], v[156:159], v[192:195], v[122:125]
	v_mfma_f32_16x16x32_bf16 v[118:121], v[148:151], v[216:219], v[118:121]
	v_mfma_f32_16x16x32_bf16 v[114:117], v[156:159], v[216:219], v[114:117]
	v_mfma_f32_16x16x32_bf16 v[102:105], v[148:151], v[224:227], v[102:105]
	v_mfma_f32_16x16x32_bf16 v[98:101], v[156:159], v[224:227], v[98:101]
	v_mfma_f32_16x16x32_bf16 v[86:89], v[148:151], v[232:235], v[86:89]
	v_mfma_f32_16x16x32_bf16 v[82:85], v[156:159], v[232:235], v[82:85]
	s_setprio 0
	s_setprio 1
	v_mfma_f32_16x16x32_bf16 v[110:113], v[160:163], v[188:191], v[110:113]
	v_mfma_f32_16x16x32_bf16 v[106:109], v[168:171], v[188:191], v[106:109]
	v_mfma_f32_16x16x32_bf16 v[94:97], v[160:163], v[212:215], v[94:97]
	v_mfma_f32_16x16x32_bf16 v[90:93], v[168:171], v[212:215], v[90:93]
	v_mfma_f32_16x16x32_bf16 v[78:81], v[160:163], v[220:223], v[78:81]
	v_mfma_f32_16x16x32_bf16 v[74:77], v[168:171], v[220:223], v[74:77]
	v_mfma_f32_16x16x32_bf16 v[70:73], v[160:163], v[228:231], v[70:73]
	v_mfma_f32_16x16x32_bf16 v[66:69], v[168:171], v[228:231], v[66:69]
	v_mfma_f32_16x16x32_bf16 v[110:113], v[164:167], v[192:195], v[110:113]
	v_mfma_f32_16x16x32_bf16 v[106:109], v[172:175], v[192:195], v[106:109]
	v_mfma_f32_16x16x32_bf16 v[94:97], v[164:167], v[216:219], v[94:97]
	v_mfma_f32_16x16x32_bf16 v[90:93], v[172:175], v[216:219], v[90:93]
	v_mfma_f32_16x16x32_bf16 v[78:81], v[164:167], v[224:227], v[78:81]
	v_mfma_f32_16x16x32_bf16 v[74:77], v[172:175], v[224:227], v[74:77]
	v_mfma_f32_16x16x32_bf16 v[70:73], v[164:167], v[232:235], v[70:73]
	v_mfma_f32_16x16x32_bf16 v[66:69], v[172:175], v[232:235], v[66:69]
	s_setprio 0
	s_barrier
	s_add_i32 s73, s73, s30
	v_lshl_add_u64 v[206:207], s[74:75], 0, v[0:1]
	s_mov_b32 m0, s73
	ds_read_b128 v[188:191], v143 offset:16384
	ds_read_b128 v[192:195], v143 offset:17408
	ds_read_b128 v[212:215], v143 offset:18432
	ds_read_b128 v[216:219], v143 offset:19456
	ds_read_b128 v[220:223], v143 offset:20480
	ds_read_b128 v[224:227], v143 offset:21504
	ds_read_b128 v[228:231], v143 offset:22528
	ds_read_b128 v[232:235], v143 offset:23552
	global_load_lds_dwordx4 v[206:207], off
	s_add_i32 m0, s73, 0x2000
	v_lshl_add_u64 v[236:237], s[74:75], 0, v[130:131]
	s_add_u32 s74, s74, s10
	s_addc_u32 s75, s75, 0
	s_add_i32 s71, s71, s30
	global_load_lds_dwordx4 v[236:237], off
	v_lshl_add_u64 v[238:239], s[74:75], 0, v[0:1]
	s_mov_b32 m0, s71
	v_lshl_add_u64 v[240:241], s[74:75], 0, v[130:131]
	global_load_lds_dwordx4 v[238:239], off
	s_add_i32 m0, s71, 0x2000
	v_lshl_add_u64 v[242:243], s[26:27], 0, v[134:135]
	global_load_lds_dwordx4 v[240:241], off
	s_mov_b32 m0, s34
	v_lshl_add_u64 v[244:245], s[26:27], 0, v[132:133]
	global_load_lds_dwordx4 v[242:243], off
	s_mov_b32 m0, s35
	s_nop 0
	global_load_lds_dwordx4 v[244:245], off
	s_waitcnt vmcnt(8)
	s_waitcnt lgkmcnt(0)
	s_barrier
	s_setprio 1
	s_waitcnt lgkmcnt(0)
	v_mfma_f32_16x16x32_bf16 v[62:65], v[144:147], v[188:191], v[62:65]
	v_mfma_f32_16x16x32_bf16 v[58:61], v[152:155], v[188:191], v[58:61]
	v_mfma_f32_16x16x32_bf16 v[54:57], v[144:147], v[212:215], v[54:57]
	v_mfma_f32_16x16x32_bf16 v[50:53], v[152:155], v[212:215], v[50:53]
	v_mfma_f32_16x16x32_bf16 v[38:41], v[144:147], v[220:223], v[38:41]
	v_mfma_f32_16x16x32_bf16 v[34:37], v[152:155], v[220:223], v[34:37]
	v_mfma_f32_16x16x32_bf16 v[22:25], v[144:147], v[228:231], v[22:25]
	v_mfma_f32_16x16x32_bf16 v[18:21], v[152:155], v[228:231], v[18:21]
	v_mfma_f32_16x16x32_bf16 v[62:65], v[148:151], v[192:195], v[62:65]
	v_mfma_f32_16x16x32_bf16 v[58:61], v[156:159], v[192:195], v[58:61]
	v_mfma_f32_16x16x32_bf16 v[54:57], v[148:151], v[216:219], v[54:57]
	v_mfma_f32_16x16x32_bf16 v[50:53], v[156:159], v[216:219], v[50:53]
	v_mfma_f32_16x16x32_bf16 v[38:41], v[148:151], v[224:227], v[38:41]
	v_mfma_f32_16x16x32_bf16 v[34:37], v[156:159], v[224:227], v[34:37]
	v_mfma_f32_16x16x32_bf16 v[22:25], v[148:151], v[232:235], v[22:25]
	v_mfma_f32_16x16x32_bf16 v[18:21], v[156:159], v[232:235], v[18:21]
	s_setprio 0
	s_setprio 1
	v_mfma_f32_16x16x32_bf16 v[46:49], v[160:163], v[188:191], v[46:49]
	v_mfma_f32_16x16x32_bf16 v[42:45], v[168:171], v[188:191], v[42:45]
	v_mfma_f32_16x16x32_bf16 v[30:33], v[160:163], v[212:215], v[30:33]
	v_mfma_f32_16x16x32_bf16 v[26:29], v[168:171], v[212:215], v[26:29]
	v_mfma_f32_16x16x32_bf16 v[14:17], v[160:163], v[220:223], v[14:17]
	v_mfma_f32_16x16x32_bf16 v[10:13], v[168:171], v[220:223], v[10:13]
	v_mfma_f32_16x16x32_bf16 v[6:9], v[160:163], v[228:231], v[6:9]
	v_mfma_f32_16x16x32_bf16 v[2:5], v[168:171], v[228:231], v[2:5]
	v_mfma_f32_16x16x32_bf16 v[46:49], v[164:167], v[192:195], v[46:49]
	v_mfma_f32_16x16x32_bf16 v[42:45], v[172:175], v[192:195], v[42:45]
	v_mfma_f32_16x16x32_bf16 v[30:33], v[164:167], v[216:219], v[30:33]
	v_mfma_f32_16x16x32_bf16 v[26:29], v[172:175], v[216:219], v[26:29]
	v_mfma_f32_16x16x32_bf16 v[14:17], v[164:167], v[224:227], v[14:17]
	v_mfma_f32_16x16x32_bf16 v[10:13], v[172:175], v[224:227], v[10:13]
	v_mfma_f32_16x16x32_bf16 v[6:9], v[164:167], v[232:235], v[6:9]
	v_mfma_f32_16x16x32_bf16 v[2:5], v[172:175], v[232:235], v[2:5]
	s_setprio 0
	s_barrier
	s_add_i32 s71, 0, 0x18000
	s_add_i32 s73, 0, 0x1c000
	v_add_u32_e32 v156, s71, v141
	v_add_u32_e32 v172, s73, v141
	ds_read_b128 v[144:147], v156
	ds_read_b128 v[148:151], v156 offset:1024
	ds_read_b128 v[152:155], v156 offset:2048
	ds_read_b128 v[156:159], v156 offset:3072
	ds_read_b128 v[160:163], v172
	ds_read_b128 v[164:167], v172 offset:1024
	ds_read_b128 v[168:171], v172 offset:2048
	ds_read_b128 v[172:175], v172 offset:3072
	s_add_u32 s26, s26, s10
	s_addc_u32 s27, s27, 0
	s_mov_b32 m0, s36
	v_lshl_add_u64 v[246:247], s[26:27], 0, v[134:135]
	ds_read_b128 v[188:191], v143 offset:32768
	ds_read_b128 v[192:195], v143 offset:33792
	ds_read_b128 v[212:215], v143 offset:34816
	ds_read_b128 v[216:219], v143 offset:35840
	ds_read_b128 v[220:223], v143 offset:36864
	ds_read_b128 v[224:227], v143 offset:37888
	ds_read_b128 v[228:231], v143 offset:38912
	ds_read_b128 v[232:235], v143 offset:39936
	global_load_lds_dwordx4 v[246:247], off
	v_lshl_add_u64 v[246:247], s[26:27], 0, v[132:133]
	s_mov_b32 m0, s37
	s_nop 0
	global_load_lds_dwordx4 v[246:247], off
	s_waitcnt vmcnt(8)
	s_waitcnt lgkmcnt(0)
	s_barrier
	s_setprio 1
	s_waitcnt lgkmcnt(0)
	v_mfma_f32_16x16x32_bf16 v[126:129], v[144:147], v[188:191], v[126:129]
	v_mfma_f32_16x16x32_bf16 v[122:125], v[152:155], v[188:191], v[122:125]
	v_mfma_f32_16x16x32_bf16 v[118:121], v[144:147], v[212:215], v[118:121]
	v_mfma_f32_16x16x32_bf16 v[114:117], v[152:155], v[212:215], v[114:117]
	v_mfma_f32_16x16x32_bf16 v[102:105], v[144:147], v[220:223], v[102:105]
	v_mfma_f32_16x16x32_bf16 v[98:101], v[152:155], v[220:223], v[98:101]
	v_mfma_f32_16x16x32_bf16 v[86:89], v[144:147], v[228:231], v[86:89]
	v_mfma_f32_16x16x32_bf16 v[82:85], v[152:155], v[228:231], v[82:85]
	v_mfma_f32_16x16x32_bf16 v[126:129], v[148:151], v[192:195], v[126:129]
	v_mfma_f32_16x16x32_bf16 v[122:125], v[156:159], v[192:195], v[122:125]
	v_mfma_f32_16x16x32_bf16 v[118:121], v[148:151], v[216:219], v[118:121]
	v_mfma_f32_16x16x32_bf16 v[114:117], v[156:159], v[216:219], v[114:117]
	v_mfma_f32_16x16x32_bf16 v[102:105], v[148:151], v[224:227], v[102:105]
	v_mfma_f32_16x16x32_bf16 v[98:101], v[156:159], v[224:227], v[98:101]
	v_mfma_f32_16x16x32_bf16 v[86:89], v[148:151], v[232:235], v[86:89]
	v_mfma_f32_16x16x32_bf16 v[82:85], v[156:159], v[232:235], v[82:85]
	s_setprio 0
	s_setprio 1
	v_mfma_f32_16x16x32_bf16 v[110:113], v[160:163], v[188:191], v[110:113]
	v_mfma_f32_16x16x32_bf16 v[106:109], v[168:171], v[188:191], v[106:109]
	v_mfma_f32_16x16x32_bf16 v[94:97], v[160:163], v[212:215], v[94:97]
	v_mfma_f32_16x16x32_bf16 v[90:93], v[168:171], v[212:215], v[90:93]
	v_mfma_f32_16x16x32_bf16 v[78:81], v[160:163], v[220:223], v[78:81]
	v_mfma_f32_16x16x32_bf16 v[74:77], v[168:171], v[220:223], v[74:77]
	v_mfma_f32_16x16x32_bf16 v[70:73], v[160:163], v[228:231], v[70:73]
	v_mfma_f32_16x16x32_bf16 v[66:69], v[168:171], v[228:231], v[66:69]
	v_mfma_f32_16x16x32_bf16 v[110:113], v[164:167], v[192:195], v[110:113]
	v_mfma_f32_16x16x32_bf16 v[106:109], v[172:175], v[192:195], v[106:109]
	v_mfma_f32_16x16x32_bf16 v[94:97], v[164:167], v[216:219], v[94:97]
	v_mfma_f32_16x16x32_bf16 v[90:93], v[172:175], v[216:219], v[90:93]
	v_mfma_f32_16x16x32_bf16 v[78:81], v[164:167], v[224:227], v[78:81]
	v_mfma_f32_16x16x32_bf16 v[74:77], v[172:175], v[224:227], v[74:77]
	v_mfma_f32_16x16x32_bf16 v[70:73], v[164:167], v[232:235], v[70:73]
	v_mfma_f32_16x16x32_bf16 v[66:69], v[172:175], v[232:235], v[66:69]
	s_setprio 0
	s_barrier
	s_add_i32 s26, s71, s30
	v_lshl_add_u64 v[206:207], v[206:207], 0, s[68:69]
	s_mov_b32 m0, s26
	ds_read_b128 v[188:191], v143 offset:49152
	ds_read_b128 v[192:195], v143 offset:50176
	ds_read_b128 v[212:215], v143 offset:51200
	ds_read_b128 v[216:219], v143 offset:52224
	ds_read_b128 v[220:223], v143 offset:53248
	ds_read_b128 v[224:227], v143 offset:54272
	ds_read_b128 v[228:231], v143 offset:55296
	ds_read_b128 v[232:235], v143 offset:56320
	global_load_lds_dwordx4 v[206:207], off
	v_lshl_add_u64 v[206:207], v[236:237], 0, s[68:69]
	s_add_i32 m0, s26, 0x2000
	s_add_i32 s26, s73, s30
	global_load_lds_dwordx4 v[206:207], off
	v_lshl_add_u64 v[206:207], v[238:239], 0, s[68:69]
	s_mov_b32 m0, s26
	s_nop 0
	global_load_lds_dwordx4 v[206:207], off
	v_lshl_add_u64 v[206:207], v[240:241], 0, s[68:69]
	s_add_i32 m0, s26, 0x2000
	s_nop 0
	global_load_lds_dwordx4 v[206:207], off
	v_lshl_add_u64 v[206:207], v[242:243], 0, s[68:69]
	s_mov_b32 m0, s38
	s_nop 0
	global_load_lds_dwordx4 v[206:207], off
	v_lshl_add_u64 v[206:207], v[244:245], 0, s[68:69]
	s_mov_b32 m0, s39
	s_nop 0
	global_load_lds_dwordx4 v[206:207], off
	s_waitcnt vmcnt(8)
	s_waitcnt lgkmcnt(0)
	s_barrier
	s_setprio 1
	s_waitcnt lgkmcnt(0)
	v_mfma_f32_16x16x32_bf16 v[62:65], v[144:147], v[188:191], v[62:65]
	v_mfma_f32_16x16x32_bf16 v[58:61], v[152:155], v[188:191], v[58:61]
	v_mfma_f32_16x16x32_bf16 v[54:57], v[144:147], v[212:215], v[54:57]
	v_mfma_f32_16x16x32_bf16 v[50:53], v[152:155], v[212:215], v[50:53]
	v_mfma_f32_16x16x32_bf16 v[38:41], v[144:147], v[220:223], v[38:41]
	v_mfma_f32_16x16x32_bf16 v[34:37], v[152:155], v[220:223], v[34:37]
	v_mfma_f32_16x16x32_bf16 v[22:25], v[144:147], v[228:231], v[22:25]
	v_mfma_f32_16x16x32_bf16 v[18:21], v[152:155], v[228:231], v[18:21]
	v_mfma_f32_16x16x32_bf16 v[62:65], v[148:151], v[192:195], v[62:65]
	v_mfma_f32_16x16x32_bf16 v[58:61], v[156:159], v[192:195], v[58:61]
	v_mfma_f32_16x16x32_bf16 v[54:57], v[148:151], v[216:219], v[54:57]
	v_mfma_f32_16x16x32_bf16 v[50:53], v[156:159], v[216:219], v[50:53]
	v_mfma_f32_16x16x32_bf16 v[38:41], v[148:151], v[224:227], v[38:41]
	v_mfma_f32_16x16x32_bf16 v[34:37], v[156:159], v[224:227], v[34:37]
	v_mfma_f32_16x16x32_bf16 v[22:25], v[148:151], v[232:235], v[22:25]
	v_mfma_f32_16x16x32_bf16 v[18:21], v[156:159], v[232:235], v[18:21]
	s_setprio 0
	s_setprio 1
	v_mfma_f32_16x16x32_bf16 v[46:49], v[160:163], v[188:191], v[46:49]
	v_mfma_f32_16x16x32_bf16 v[42:45], v[168:171], v[188:191], v[42:45]
	v_mfma_f32_16x16x32_bf16 v[30:33], v[160:163], v[212:215], v[30:33]
	v_mfma_f32_16x16x32_bf16 v[26:29], v[168:171], v[212:215], v[26:29]
	v_mfma_f32_16x16x32_bf16 v[14:17], v[160:163], v[220:223], v[14:17]
	v_mfma_f32_16x16x32_bf16 v[10:13], v[168:171], v[220:223], v[10:13]
	v_mfma_f32_16x16x32_bf16 v[6:9], v[160:163], v[228:231], v[6:9]
	v_mfma_f32_16x16x32_bf16 v[2:5], v[168:171], v[228:231], v[2:5]
	v_mfma_f32_16x16x32_bf16 v[46:49], v[164:167], v[192:195], v[46:49]
	v_mfma_f32_16x16x32_bf16 v[42:45], v[172:175], v[192:195], v[42:45]
	v_mfma_f32_16x16x32_bf16 v[30:33], v[164:167], v[216:219], v[30:33]
	v_mfma_f32_16x16x32_bf16 v[26:29], v[172:175], v[216:219], v[26:29]
	v_mfma_f32_16x16x32_bf16 v[14:17], v[164:167], v[224:227], v[14:17]
	v_mfma_f32_16x16x32_bf16 v[10:13], v[172:175], v[224:227], v[10:13]
	v_mfma_f32_16x16x32_bf16 v[6:9], v[164:167], v[232:235], v[6:9]
	v_mfma_f32_16x16x32_bf16 v[2:5], v[172:175], v[232:235], v[2:5]
	s_add_u32 s24, s24, 0x100
	s_addc_u32 s25, s25, 0
	s_add_u32 s57, s57, 0x100
	s_addc_u32 s63, s63, 0
	s_setprio 0
	s_barrier
	s_cmp_ge_u32 s70, s40
	s_mov_b32 s26, s70
	s_cbranch_scc0 .LBB0_743
	s_and_b64 vcc, exec, s[58:59]
	s_cbranch_vccz .LBB0_746
	s_barrier

.LBB0_918:
	s_add_u32 s26, s24, 0xfffc0080
	s_addc_u32 s27, s25, -1
	s_add_i32 s70, 0, 0x10000
	s_cmp_eq_u32 s57, 12
	s_cselect_b32 s29, s41, s27
	s_cselect_b32 s28, s42, s26
	v_add_u32_e32 v140, s70, v143
	s_cselect_b32 s27, s43, s51
	s_cselect_b32 s26, s44, s45
	s_add_i32 s73, 0, 0x14000
	ds_read_b128 v[146:149], v140
	ds_read_b128 v[150:153], v140 offset:1024
	ds_read_b128 v[154:157], v140 offset:2048
	ds_read_b128 v[158:161], v140 offset:3072
	v_add_u32_e32 v140, s73, v143
	ds_read_b128 v[162:165], v140
	ds_read_b128 v[166:169], v140 offset:1024
	ds_read_b128 v[170:173], v140 offset:2048
	ds_read_b128 v[188:191], v140 offset:3072
	v_lshl_add_u64 v[140:141], s[24:25], 0, v[136:137]
	s_add_i32 m0, s31, 0xc000
	ds_read_b128 v[192:195], v145
	ds_read_b128 v[212:215], v145 offset:1024
	ds_read_b128 v[216:219], v145 offset:2048
	ds_read_b128 v[220:223], v145 offset:3072
	ds_read_b128 v[224:227], v145 offset:4096
	ds_read_b128 v[228:231], v145 offset:5120
	ds_read_b128 v[232:235], v145 offset:6144
	ds_read_b128 v[236:239], v145 offset:7168
	global_load_lds_dwordx4 v[140:141], off
	v_lshl_add_u64 v[140:141], s[24:25], 0, v[138:139]
	s_add_i32 m0, s31, 0xe000
	s_nop 0
	global_load_lds_dwordx4 v[140:141], off
	s_waitcnt vmcnt(8)
	s_waitcnt lgkmcnt(0)
	s_barrier
	s_setprio 1
	s_waitcnt lgkmcnt(0)
	v_mfma_f32_16x16x32_bf16 v[126:129], v[146:149], v[192:195], v[126:129]
	v_mfma_f32_16x16x32_bf16 v[122:125], v[154:157], v[192:195], v[122:125]
	v_mfma_f32_16x16x32_bf16 v[110:113], v[146:149], v[216:219], v[110:113]
	v_mfma_f32_16x16x32_bf16 v[106:109], v[154:157], v[216:219], v[106:109]
	v_mfma_f32_16x16x32_bf16 v[94:97], v[146:149], v[224:227], v[94:97]
	v_mfma_f32_16x16x32_bf16 v[90:93], v[154:157], v[224:227], v[90:93]
	v_mfma_f32_16x16x32_bf16 v[78:81], v[146:149], v[232:235], v[78:81]
	v_mfma_f32_16x16x32_bf16 v[74:77], v[154:157], v[232:235], v[74:77]
	v_mfma_f32_16x16x32_bf16 v[126:129], v[150:153], v[212:215], v[126:129]
	v_mfma_f32_16x16x32_bf16 v[122:125], v[158:161], v[212:215], v[122:125]
	v_mfma_f32_16x16x32_bf16 v[110:113], v[150:153], v[220:223], v[110:113]
	v_mfma_f32_16x16x32_bf16 v[106:109], v[158:161], v[220:223], v[106:109]
	v_mfma_f32_16x16x32_bf16 v[94:97], v[150:153], v[228:231], v[94:97]
	v_mfma_f32_16x16x32_bf16 v[90:93], v[158:161], v[228:231], v[90:93]
	v_mfma_f32_16x16x32_bf16 v[78:81], v[150:153], v[236:239], v[78:81]
	v_mfma_f32_16x16x32_bf16 v[74:77], v[158:161], v[236:239], v[74:77]
	s_setprio 0
	s_setprio 1
	v_mfma_f32_16x16x32_bf16 v[118:121], v[162:165], v[192:195], v[118:121]
	v_mfma_f32_16x16x32_bf16 v[114:117], v[170:173], v[192:195], v[114:117]
	v_mfma_f32_16x16x32_bf16 v[102:105], v[162:165], v[216:219], v[102:105]
	v_mfma_f32_16x16x32_bf16 v[98:101], v[170:173], v[216:219], v[98:101]
	v_mfma_f32_16x16x32_bf16 v[86:89], v[162:165], v[224:227], v[86:89]
	v_mfma_f32_16x16x32_bf16 v[82:85], v[170:173], v[224:227], v[82:85]
	v_mfma_f32_16x16x32_bf16 v[70:73], v[162:165], v[232:235], v[70:73]
	v_mfma_f32_16x16x32_bf16 v[66:69], v[170:173], v[232:235], v[66:69]
	v_mfma_f32_16x16x32_bf16 v[118:121], v[166:169], v[212:215], v[118:121]
	v_mfma_f32_16x16x32_bf16 v[114:117], v[188:191], v[212:215], v[114:117]
	v_mfma_f32_16x16x32_bf16 v[102:105], v[166:169], v[220:223], v[102:105]
	v_mfma_f32_16x16x32_bf16 v[98:101], v[188:191], v[220:223], v[98:101]
	v_mfma_f32_16x16x32_bf16 v[86:89], v[166:169], v[228:231], v[86:89]
	v_mfma_f32_16x16x32_bf16 v[82:85], v[188:191], v[228:231], v[82:85]
	v_mfma_f32_16x16x32_bf16 v[70:73], v[166:169], v[236:239], v[70:73]
	v_mfma_f32_16x16x32_bf16 v[66:69], v[188:191], v[236:239], v[66:69]
	s_setprio 0
	s_barrier
	s_add_i32 s70, s70, s23
	v_lshl_add_u64 v[140:141], s[26:27], 0, v[0:1]
	s_mov_b32 m0, s70
	ds_read_b128 v[192:195], v145 offset:16384
	ds_read_b128 v[212:215], v145 offset:17408
	ds_read_b128 v[216:219], v145 offset:18432
	ds_read_b128 v[220:223], v145 offset:19456
	ds_read_b128 v[224:227], v145 offset:20480
	ds_read_b128 v[228:231], v145 offset:21504
	ds_read_b128 v[232:235], v145 offset:22528
	ds_read_b128 v[236:239], v145 offset:23552
	global_load_lds_dwordx4 v[140:141], off
	s_add_i32 m0, s70, 0x2000
	s_add_u32 s70, s26, 0x40000
	v_lshl_add_u64 v[174:175], s[26:27], 0, v[130:131]
	s_addc_u32 s71, s27, 0
	s_add_i32 s73, s73, s23
	global_load_lds_dwordx4 v[174:175], off
	v_lshl_add_u64 v[206:207], s[70:71], 0, v[0:1]
	s_mov_b32 m0, s73
	v_lshl_add_u64 v[240:241], s[28:29], 0, v[132:133]
	global_load_lds_dwordx4 v[206:207], off
	v_lshl_add_u64 v[206:207], s[70:71], 0, v[130:131]
	s_add_i32 m0, s73, 0x2000
	s_nop 0
	global_load_lds_dwordx4 v[206:207], off
	v_lshl_add_u64 v[206:207], s[28:29], 0, v[134:135]
	s_mov_b32 m0, s31
	s_nop 0
	global_load_lds_dwordx4 v[206:207], off
	s_mov_b32 m0, s34
	s_nop 0
	global_load_lds_dwordx4 v[240:241], off
	s_waitcnt vmcnt(8)
	s_waitcnt lgkmcnt(0)
	s_barrier
; #define PG8_STAGE(bufoff, gbase, voff) do { _Pragma("unroll") for (int _i = 0; _i < 2; ++_i) \
;         __builtin_amdgcn_global_load_lds((const unsigned*)((const char*)(gbase) + (voff)[_i]), (PG8_LAS unsigned*)(lds + (bufoff) + ldsw + _i * 8192), 16, 0, 0); } while (0)
; #define PG8_LDA(dst, b, h) do { _Pragma("unroll") for (int m = 0; m < 4; ++m) _Pragma("unroll") for (int k = 0; k < 2; ++k) dst[m][k] = *(const PG8_LAS bf16x8*)(lds + PG8_SA(b, h) + aoff + m * 2048 + k * 1024); } while (0)
; #define PG8_LDB(dst, b, h) do { _Pragma("unroll") for (int n = 0; n < 2; ++n) _Pragma("unroll") for (int k = 0; k < 2; ++k) dst[n][k] = *(const PG8_LAS bf16x8*)(lds + PG8_SB(b, h) + boff + n * 2048 + k * 1024); } while (0)
; #define PG8_MMA(ai, bj, At, Bt) do { __builtin_amdgcn_s_setprio(1); _Pragma("unroll") for (int m = 0; m < 4; ++m) _Pragma("unroll") for (int n = 0; n < 2; ++n) _Pragma("unroll") for (int k = 0; k < 2; ++k) \
;         acc[ai][bj][m][n] = __builtin_amdgcn_mfma_f32_16x16x32_bf16(Bt[n][k], At[m][k], acc[ai][bj][m][n], 0, 0, 0); __builtin_amdgcn_s_setprio(0); } while (0)
; #define PG8_WAIT_V(n) asm volatile("s_waitcnt vmcnt(" #n ")" ::: "memory")
; #define PG8_WAIT_L(n) asm volatile("s_waitcnt lgkmcnt(" #n ")" ::: "memory")
; #define PG8_BAR __builtin_amdgcn_s_barrier()
; #define PG8_SCHED __builtin_amdgcn_sched_barrier(0)
; template <class Epi, class Sched, bool ALIGN_EPI = false, bool SP2 = false>
; __device__ __forceinline__ void gemm_phase(PG8_LAS unsigned char* lds, const Gemm g, const Sched& S, const Epi& E, int wave_s) {
;     ...
;             PG8_WAIT_V(8); PG8_WAIT_L(0); PG8_BAR; PG8_MMA(1, 0, At, B0); PG8_MMA(1, 1, At, B1); PG8_BAR; PG8_SCHED;
;             PG8_LDB(B0, 1, 0); PG8_LDB(B1, 1, 1); PG8_SCHED; PG8_LDA(At, 1, 0); PG8_STAGE(PG8_SA(0, 1), a2 + hstep, voffA);
;             PG8_WAIT_V(8); PG8_WAIT_L(0); PG8_BAR; PG8_MMA(0, 0, At, B0); PG8_MMA(0, 1, At, B1); PG8_BAR; PG8_SCHED;
	s_setprio 1
	s_waitcnt lgkmcnt(0)
	v_mfma_f32_16x16x32_bf16 v[62:65], v[146:149], v[192:195], v[62:65]
	v_mfma_f32_16x16x32_bf16 v[58:61], v[154:157], v[192:195], v[58:61]
	v_mfma_f32_16x16x32_bf16 v[46:49], v[146:149], v[216:219], v[46:49]
	v_mfma_f32_16x16x32_bf16 v[42:45], v[154:157], v[216:219], v[42:45]
	v_mfma_f32_16x16x32_bf16 v[30:33], v[146:149], v[224:227], v[30:33]
	v_mfma_f32_16x16x32_bf16 v[26:29], v[154:157], v[224:227], v[26:29]
	v_mfma_f32_16x16x32_bf16 v[14:17], v[146:149], v[232:235], v[14:17]
	v_mfma_f32_16x16x32_bf16 v[10:13], v[154:157], v[232:235], v[10:13]
	v_mfma_f32_16x16x32_bf16 v[62:65], v[150:153], v[212:215], v[62:65]
	v_mfma_f32_16x16x32_bf16 v[58:61], v[158:161], v[212:215], v[58:61]
	v_mfma_f32_16x16x32_bf16 v[46:49], v[150:153], v[220:223], v[46:49]
	v_mfma_f32_16x16x32_bf16 v[42:45], v[158:161], v[220:223], v[42:45]
	v_mfma_f32_16x16x32_bf16 v[30:33], v[150:153], v[228:231], v[30:33]
	v_mfma_f32_16x16x32_bf16 v[26:29], v[158:161], v[228:231], v[26:29]
	v_mfma_f32_16x16x32_bf16 v[14:17], v[150:153], v[236:239], v[14:17]
	v_mfma_f32_16x16x32_bf16 v[10:13], v[158:161], v[236:239], v[10:13]
	s_setprio 0
	s_setprio 1
	v_mfma_f32_16x16x32_bf16 v[54:57], v[162:165], v[192:195], v[54:57]
	v_mfma_f32_16x16x32_bf16 v[50:53], v[170:173], v[192:195], v[50:53]
	v_mfma_f32_16x16x32_bf16 v[38:41], v[162:165], v[216:219], v[38:41]
	v_mfma_f32_16x16x32_bf16 v[34:37], v[170:173], v[216:219], v[34:37]
	v_mfma_f32_16x16x32_bf16 v[22:25], v[162:165], v[224:227], v[22:25]
	v_mfma_f32_16x16x32_bf16 v[18:21], v[170:173], v[224:227], v[18:21]
	v_mfma_f32_16x16x32_bf16 v[6:9], v[162:165], v[232:235], v[6:9]
	v_mfma_f32_16x16x32_bf16 v[2:5], v[170:173], v[232:235], v[2:5]
	v_mfma_f32_16x16x32_bf16 v[54:57], v[166:169], v[212:215], v[54:57]
	v_mfma_f32_16x16x32_bf16 v[50:53], v[188:191], v[212:215], v[50:53]
	v_mfma_f32_16x16x32_bf16 v[38:41], v[166:169], v[220:223], v[38:41]
	v_mfma_f32_16x16x32_bf16 v[34:37], v[188:191], v[220:223], v[34:37]
	v_mfma_f32_16x16x32_bf16 v[22:25], v[166:169], v[228:231], v[22:25]
	v_mfma_f32_16x16x32_bf16 v[18:21], v[188:191], v[228:231], v[18:21]
	v_mfma_f32_16x16x32_bf16 v[6:9], v[166:169], v[236:239], v[6:9]
	v_mfma_f32_16x16x32_bf16 v[2:5], v[188:191], v[236:239], v[2:5]
	s_setprio 0
	s_barrier
	s_add_i32 s70, 0, 0x18000
	s_add_i32 s71, 0, 0x1c000
	v_add_u32_e32 v158, s70, v143
	v_add_u32_e32 v176, s71, v143
	ds_read_b128 v[146:149], v158
	ds_read_b128 v[150:153], v158 offset:1024
	ds_read_b128 v[154:157], v158 offset:2048
	ds_read_b128 v[158:161], v158 offset:3072
	ds_read_b128 v[162:165], v176
	ds_read_b128 v[166:169], v176 offset:1024
	ds_read_b128 v[170:173], v176 offset:2048
	ds_read_b128 v[188:191], v176 offset:3072
	s_add_u32 s28, s28, 0x40000
	s_addc_u32 s29, s29, 0
	s_mov_b32 m0, s35
	v_lshl_add_u64 v[242:243], s[28:29], 0, v[134:135]
	ds_read_b128 v[192:195], v145 offset:32768
	ds_read_b128 v[212:215], v145 offset:33792
	ds_read_b128 v[216:219], v145 offset:34816
	ds_read_b128 v[220:223], v145 offset:35840
	ds_read_b128 v[224:227], v145 offset:36864
	ds_read_b128 v[228:231], v145 offset:37888
	ds_read_b128 v[232:235], v145 offset:38912
	ds_read_b128 v[236:239], v145 offset:39936
	global_load_lds_dwordx4 v[242:243], off
	v_lshl_add_u64 v[242:243], s[28:29], 0, v[132:133]
	s_mov_b32 m0, s36
	s_nop 0
	global_load_lds_dwordx4 v[242:243], off
	s_waitcnt vmcnt(8)
	s_waitcnt lgkmcnt(0)
	s_barrier
	s_setprio 1
	s_waitcnt lgkmcnt(0)
	v_mfma_f32_16x16x32_bf16 v[126:129], v[146:149], v[192:195], v[126:129]
	v_mfma_f32_16x16x32_bf16 v[122:125], v[154:157], v[192:195], v[122:125]
	v_mfma_f32_16x16x32_bf16 v[110:113], v[146:149], v[216:219], v[110:113]
	v_mfma_f32_16x16x32_bf16 v[106:109], v[154:157], v[216:219], v[106:109]
	v_mfma_f32_16x16x32_bf16 v[94:97], v[146:149], v[224:227], v[94:97]
	v_mfma_f32_16x16x32_bf16 v[90:93], v[154:157], v[224:227], v[90:93]
	v_mfma_f32_16x16x32_bf16 v[78:81], v[146:149], v[232:235], v[78:81]
	v_mfma_f32_16x16x32_bf16 v[74:77], v[154:157], v[232:235], v[74:77]
	v_mfma_f32_16x16x32_bf16 v[126:129], v[150:153], v[212:215], v[126:129]
	v_mfma_f32_16x16x32_bf16 v[122:125], v[158:161], v[212:215], v[122:125]
	v_mfma_f32_16x16x32_bf16 v[110:113], v[150:153], v[220:223], v[110:113]
	v_mfma_f32_16x16x32_bf16 v[106:109], v[158:161], v[220:223], v[106:109]
	v_mfma_f32_16x16x32_bf16 v[94:97], v[150:153], v[228:231], v[94:97]
	v_mfma_f32_16x16x32_bf16 v[90:93], v[158:161], v[228:231], v[90:93]
	v_mfma_f32_16x16x32_bf16 v[78:81], v[150:153], v[236:239], v[78:81]
	v_mfma_f32_16x16x32_bf16 v[74:77], v[158:161], v[236:239], v[74:77]
	s_setprio 0
	s_setprio 1
	v_mfma_f32_16x16x32_bf16 v[118:121], v[162:165], v[192:195], v[118:121]
	v_mfma_f32_16x16x32_bf16 v[114:117], v[170:173], v[192:195], v[114:117]
	v_mfma_f32_16x16x32_bf16 v[102:105], v[162:165], v[216:219], v[102:105]
	v_mfma_f32_16x16x32_bf16 v[98:101], v[170:173], v[216:219], v[98:101]
	v_mfma_f32_16x16x32_bf16 v[86:89], v[162:165], v[224:227], v[86:89]
	v_mfma_f32_16x16x32_bf16 v[82:85], v[170:173], v[224:227], v[82:85]
	v_mfma_f32_16x16x32_bf16 v[70:73], v[162:165], v[232:235], v[70:73]
	v_mfma_f32_16x16x32_bf16 v[66:69], v[170:173], v[232:235], v[66:69]
	v_mfma_f32_16x16x32_bf16 v[118:121], v[166:169], v[212:215], v[118:121]
	v_mfma_f32_16x16x32_bf16 v[114:117], v[188:191], v[212:215], v[114:117]
	v_mfma_f32_16x16x32_bf16 v[102:105], v[166:169], v[220:223], v[102:105]
	v_mfma_f32_16x16x32_bf16 v[98:101], v[188:191], v[220:223], v[98:101]
	v_mfma_f32_16x16x32_bf16 v[86:89], v[166:169], v[228:231], v[86:89]
	v_mfma_f32_16x16x32_bf16 v[82:85], v[188:191], v[228:231], v[82:85]
	v_mfma_f32_16x16x32_bf16 v[70:73], v[166:169], v[236:239], v[70:73]
	v_mfma_f32_16x16x32_bf16 v[66:69], v[188:191], v[236:239], v[66:69]
	s_setprio 0
	s_barrier
; #define PG8_STAGE(bufoff, gbase, voff) do { _Pragma("unroll") for (int _i = 0; _i < 2; ++_i) \
;         __builtin_amdgcn_global_load_lds((const unsigned*)((const char*)(gbase) + (voff)[_i]), (PG8_LAS unsigned*)(lds + (bufoff) + ldsw + _i * 8192), 16, 0, 0); } while (0)
; #define PG8_LDA(dst, b, h) do { _Pragma("unroll") for (int m = 0; m < 4; ++m) _Pragma("unroll") for (int k = 0; k < 2; ++k) dst[m][k] = *(const PG8_LAS bf16x8*)(lds + PG8_SA(b, h) + aoff + m * 2048 + k * 1024); } while (0)
; #define PG8_MMA(ai, bj, At, Bt) do { __builtin_amdgcn_s_setprio(1); _Pragma("unroll") for (int m = 0; m < 4; ++m) _Pragma("unroll") for (int n = 0; n < 2; ++n) _Pragma("unroll") for (int k = 0; k < 2; ++k) \
;         acc[ai][bj][m][n] = __builtin_amdgcn_mfma_f32_16x16x32_bf16(Bt[n][k], At[m][k], acc[ai][bj][m][n], 0, 0, 0); __builtin_amdgcn_s_setprio(0); } while (0)
; #define PG8_WAIT_V(n) asm volatile("s_waitcnt vmcnt(" #n ")" ::: "memory")
; #define PG8_WAIT_L(n) asm volatile("s_waitcnt lgkmcnt(" #n ")" ::: "memory")
; #define PG8_BAR __builtin_amdgcn_s_barrier()
; #define PG8_SCHED __builtin_amdgcn_sched_barrier(0)
; template <class Epi, class Sched, bool ALIGN_EPI = false, bool SP2 = false>
; __device__ __forceinline__ void gemm_phase(PG8_LAS unsigned char* lds, const Gemm g, const Sched& S, const Epi& E, int wave_s) {
;     ...
;         for (int t = 0; t < nt; t += 2) {
;     ...
;             PG8_LDA(At, 1, 1); PG8_STAGE(PG8_SB(1, 0), b3, voffB); PG8_STAGE(PG8_SB(1, 1), b3 + hstep, voffB); PG8_STAGE(PG8_SA(1, 0), a3, voffA);
;             PG8_WAIT_V(8); PG8_WAIT_L(0); PG8_BAR; PG8_MMA(1, 0, At, B0); PG8_MMA(1, 1, At, B1); PG8_BAR; PG8_SCHED;
	s_add_i32 s28, s70, s23
	v_lshl_add_u64 v[140:141], v[140:141], 0, s[68:69]
	s_mov_b32 m0, s28
	ds_read_b128 v[192:195], v145 offset:49152
	ds_read_b128 v[212:215], v145 offset:50176
	ds_read_b128 v[216:219], v145 offset:51200
	ds_read_b128 v[220:223], v145 offset:52224
	ds_read_b128 v[224:227], v145 offset:53248
	ds_read_b128 v[228:231], v145 offset:54272
	ds_read_b128 v[232:235], v145 offset:55296
	ds_read_b128 v[236:239], v145 offset:56320
	global_load_lds_dwordx4 v[140:141], off
	s_add_i32 m0, s28, 0x2000
	s_add_u32 s26, s26, 0x40080
	v_lshl_add_u64 v[140:141], v[174:175], 0, s[68:69]
	s_addc_u32 s27, s27, 0
	s_add_i32 s28, s71, s23
	global_load_lds_dwordx4 v[140:141], off
	v_lshl_add_u64 v[140:141], s[26:27], 0, v[0:1]
	s_mov_b32 m0, s28
	s_nop 0
	global_load_lds_dwordx4 v[140:141], off
	v_lshl_add_u64 v[140:141], s[26:27], 0, v[130:131]
	s_add_i32 m0, s28, 0x2000
	s_nop 0
	global_load_lds_dwordx4 v[140:141], off
	v_lshl_add_u64 v[140:141], v[206:207], 0, s[68:69]
	s_mov_b32 m0, s10
	s_nop 0
	global_load_lds_dwordx4 v[140:141], off
	v_lshl_add_u64 v[140:141], v[240:241], 0, s[68:69]
	s_mov_b32 m0, s37
	s_nop 0
	global_load_lds_dwordx4 v[140:141], off
	s_waitcnt vmcnt(8)
	s_waitcnt lgkmcnt(0)
	s_barrier
	s_setprio 1
	s_waitcnt lgkmcnt(0)
	v_mfma_f32_16x16x32_bf16 v[62:65], v[146:149], v[192:195], v[62:65]
	v_mfma_f32_16x16x32_bf16 v[58:61], v[154:157], v[192:195], v[58:61]
	v_mfma_f32_16x16x32_bf16 v[46:49], v[146:149], v[216:219], v[46:49]
	v_mfma_f32_16x16x32_bf16 v[42:45], v[154:157], v[216:219], v[42:45]
	v_mfma_f32_16x16x32_bf16 v[30:33], v[146:149], v[224:227], v[30:33]
	v_mfma_f32_16x16x32_bf16 v[26:29], v[154:157], v[224:227], v[26:29]
	v_mfma_f32_16x16x32_bf16 v[14:17], v[146:149], v[232:235], v[14:17]
	v_mfma_f32_16x16x32_bf16 v[10:13], v[154:157], v[232:235], v[10:13]
	v_mfma_f32_16x16x32_bf16 v[62:65], v[150:153], v[212:215], v[62:65]
	v_mfma_f32_16x16x32_bf16 v[58:61], v[158:161], v[212:215], v[58:61]
	v_mfma_f32_16x16x32_bf16 v[46:49], v[150:153], v[220:223], v[46:49]
	v_mfma_f32_16x16x32_bf16 v[42:45], v[158:161], v[220:223], v[42:45]
	v_mfma_f32_16x16x32_bf16 v[30:33], v[150:153], v[228:231], v[30:33]
	v_mfma_f32_16x16x32_bf16 v[26:29], v[158:161], v[228:231], v[26:29]
	v_mfma_f32_16x16x32_bf16 v[14:17], v[150:153], v[236:239], v[14:17]
	v_mfma_f32_16x16x32_bf16 v[10:13], v[158:161], v[236:239], v[10:13]
	s_setprio 0
	s_setprio 1
	v_mfma_f32_16x16x32_bf16 v[54:57], v[162:165], v[192:195], v[54:57]
	v_mfma_f32_16x16x32_bf16 v[50:53], v[170:173], v[192:195], v[50:53]
	v_mfma_f32_16x16x32_bf16 v[38:41], v[162:165], v[216:219], v[38:41]
	v_mfma_f32_16x16x32_bf16 v[34:37], v[170:173], v[216:219], v[34:37]
	v_mfma_f32_16x16x32_bf16 v[22:25], v[162:165], v[224:227], v[22:25]
	v_mfma_f32_16x16x32_bf16 v[18:21], v[170:173], v[224:227], v[18:21]
	v_mfma_f32_16x16x32_bf16 v[6:9], v[162:165], v[232:235], v[6:9]
	v_mfma_f32_16x16x32_bf16 v[2:5], v[170:173], v[232:235], v[2:5]
	v_mfma_f32_16x16x32_bf16 v[54:57], v[166:169], v[212:215], v[54:57]
	v_mfma_f32_16x16x32_bf16 v[50:53], v[188:191], v[212:215], v[50:53]
	v_mfma_f32_16x16x32_bf16 v[38:41], v[166:169], v[220:223], v[38:41]
	v_mfma_f32_16x16x32_bf16 v[34:37], v[188:191], v[220:223], v[34:37]
	v_mfma_f32_16x16x32_bf16 v[22:25], v[166:169], v[228:231], v[22:25]
	v_mfma_f32_16x16x32_bf16 v[18:21], v[188:191], v[228:231], v[18:21]
	v_mfma_f32_16x16x32_bf16 v[6:9], v[166:169], v[236:239], v[6:9]
	v_mfma_f32_16x16x32_bf16 v[2:5], v[188:191], v[236:239], v[2:5]
	s_add_i32 s57, s57, 2
	s_add_u32 s24, s24, 0x100
	s_addc_u32 s25, s25, 0
	s_add_u32 s45, s45, 0x100
	s_addc_u32 s51, s51, 0
	s_setprio 0
	s_barrier
	s_cmp_gt_u32 s57, 13
	s_cbranch_scc0 .LBB0_918
	s_and_b64 vcc, exec, s[62:63]
	s_cbranch_vccz .LBB0_921
	s_barrier

; #define PG8_STAGE(bufoff, gbase, voff) do { _Pragma("unroll") for (int _i = 0; _i < 2; ++_i) \
;         __builtin_amdgcn_global_load_lds((const unsigned*)((const char*)(gbase) + (voff)[_i]), (PG8_LAS unsigned*)(lds + (bufoff) + ldsw + _i * 8192), 16, 0, 0); } while (0)
; #define PG8_LDA(dst, b, h) do { _Pragma("unroll") for (int m = 0; m < 4; ++m) _Pragma("unroll") for (int k = 0; k < 2; ++k) dst[m][k] = *(const PG8_LAS bf16x8*)(lds + PG8_SA(b, h) + aoff + m * 2048 + k * 1024); } while (0)
; #define PG8_LDB(dst, b, h) do { _Pragma("unroll") for (int n = 0; n < 2; ++n) _Pragma("unroll") for (int k = 0; k < 2; ++k) dst[n][k] = *(const PG8_LAS bf16x8*)(lds + PG8_SB(b, h) + boff + n * 2048 + k * 1024); } while (0)
; #define PG8_MMA(ai, bj, At, Bt) do { __builtin_amdgcn_s_setprio(1); _Pragma("unroll") for (int m = 0; m < 4; ++m) _Pragma("unroll") for (int n = 0; n < 2; ++n) _Pragma("unroll") for (int k = 0; k < 2; ++k) \
;         acc[ai][bj][m][n] = __builtin_amdgcn_mfma_f32_16x16x32_bf16(Bt[n][k], At[m][k], acc[ai][bj][m][n], 0, 0, 0); __builtin_amdgcn_s_setprio(0); } while (0)
; #define PG8_WAIT_V(n) asm volatile("s_waitcnt vmcnt(" #n ")" ::: "memory")
; #define PG8_WAIT_L(n) asm volatile("s_waitcnt lgkmcnt(" #n ")" ::: "memory")
; #define PG8_BAR __builtin_amdgcn_s_barrier()
; #define PG8_SCHED __builtin_amdgcn_sched_barrier(0)
; template <class Epi, class Sched, bool ALIGN_EPI = false, bool SP2 = false>
; __device__ __forceinline__ void gemm_phase(PG8_LAS unsigned char* lds, const Gemm g, const Sched& S, const Epi& E, int wave_s) {
;     ...
;             const bool last = (t == nt - 2);
;             const char* a1 = cA + (size_t)(t + 1) * kstep;
;             const char* a2 = last ? nA : cA + (size_t)(t + 2) * kstep; const char* b2 = last ? nB : cB + (size_t)(t + 2) * kstep;
;             const char* a3 = a2 + kstep; const char* b3 = b2 + kstep;
;             if (last && has_next) S.a_ready(nxt);
;             if constexpr (SP2) {
;             PG8_LDB(B0, 0, 0); PG8_LDB(B1, 0, 1); PG8_SCHED; PG8_LDA(At, 0, 0); PG8_STAGE(PG8_SA(1, 1), a1 + hstep, voffA);
;             PG8_WAIT_V(8); PG8_WAIT_L(0); PG8_BAR; PG8_MMA(0, 0, At, B0); PG8_MMA(0, 1, At, B1); PG8_BAR; PG8_SCHED;
;             PG8_LDA(At, 0, 1); PG8_STAGE(PG8_SB(0, 0), b2, voffB); PG8_STAGE(PG8_SB(0, 1), b2 + hstep, voffB); PG8_STAGE(PG8_SA(0, 0), a2, voffA);
.LBB0_986:
	s_add_u32 s26, s24, 0xfff00080
	s_addc_u32 s27, s25, -1
	s_add_i32 s63, 0, 0x10000
	s_cmp_eq_u32 s57, 60
	s_cselect_b32 s29, s41, s27
	s_cselect_b32 s28, s42, s26
	s_cselect_b32 s27, s43, s51
	s_cselect_b32 s26, s44, s45
	s_add_i32 s73, 0, 0x14000
	v_add_u32_e32 v156, s63, v141
	v_add_u32_e32 v172, s73, v141
	ds_read_b128 v[144:147], v156
	ds_read_b128 v[148:151], v156 offset:1024
	ds_read_b128 v[152:155], v156 offset:2048
	ds_read_b128 v[156:159], v156 offset:3072
	ds_read_b128 v[160:163], v172
	ds_read_b128 v[164:167], v172 offset:1024
	ds_read_b128 v[168:171], v172 offset:2048
	ds_read_b128 v[172:175], v172 offset:3072
	v_lshl_add_u64 v[206:207], s[24:25], 0, v[136:137]
	s_add_i32 m0, s30, 0xc000
	ds_read_b128 v[188:191], v143
	ds_read_b128 v[192:195], v143 offset:1024
	ds_read_b128 v[212:215], v143 offset:2048
	ds_read_b128 v[216:219], v143 offset:3072
	ds_read_b128 v[220:223], v143 offset:4096
	ds_read_b128 v[224:227], v143 offset:5120
	ds_read_b128 v[228:231], v143 offset:6144
	ds_read_b128 v[232:235], v143 offset:7168
	global_load_lds_dwordx4 v[206:207], off
	v_lshl_add_u64 v[206:207], s[24:25], 0, v[138:139]
	s_add_i32 m0, s30, 0xe000
	s_nop 0
	global_load_lds_dwordx4 v[206:207], off
	s_waitcnt vmcnt(8)
	s_waitcnt lgkmcnt(0)
	s_barrier
	s_setprio 1
	s_waitcnt lgkmcnt(0)
	v_mfma_f32_16x16x32_bf16 v[126:129], v[144:147], v[188:191], v[126:129]
	v_mfma_f32_16x16x32_bf16 v[122:125], v[152:155], v[188:191], v[122:125]
	v_mfma_f32_16x16x32_bf16 v[118:121], v[144:147], v[212:215], v[118:121]
	v_mfma_f32_16x16x32_bf16 v[114:117], v[152:155], v[212:215], v[114:117]
	v_mfma_f32_16x16x32_bf16 v[102:105], v[144:147], v[220:223], v[102:105]
	v_mfma_f32_16x16x32_bf16 v[98:101], v[152:155], v[220:223], v[98:101]
	v_mfma_f32_16x16x32_bf16 v[86:89], v[144:147], v[228:231], v[86:89]
	v_mfma_f32_16x16x32_bf16 v[82:85], v[152:155], v[228:231], v[82:85]
	v_mfma_f32_16x16x32_bf16 v[126:129], v[148:151], v[192:195], v[126:129]
	v_mfma_f32_16x16x32_bf16 v[122:125], v[156:159], v[192:195], v[122:125]
	v_mfma_f32_16x16x32_bf16 v[118:121], v[148:151], v[216:219], v[118:121]
	v_mfma_f32_16x16x32_bf16 v[114:117], v[156:159], v[216:219], v[114:117]
	v_mfma_f32_16x16x32_bf16 v[102:105], v[148:151], v[224:227], v[102:105]
	v_mfma_f32_16x16x32_bf16 v[98:101], v[156:159], v[224:227], v[98:101]
	v_mfma_f32_16x16x32_bf16 v[86:89], v[148:151], v[232:235], v[86:89]
	v_mfma_f32_16x16x32_bf16 v[82:85], v[156:159], v[232:235], v[82:85]
	s_setprio 0
	s_setprio 1
	v_mfma_f32_16x16x32_bf16 v[110:113], v[160:163], v[188:191], v[110:113]
	v_mfma_f32_16x16x32_bf16 v[106:109], v[168:171], v[188:191], v[106:109]
	v_mfma_f32_16x16x32_bf16 v[94:97], v[160:163], v[212:215], v[94:97]
	v_mfma_f32_16x16x32_bf16 v[90:93], v[168:171], v[212:215], v[90:93]
	v_mfma_f32_16x16x32_bf16 v[78:81], v[160:163], v[220:223], v[78:81]
	v_mfma_f32_16x16x32_bf16 v[74:77], v[168:171], v[220:223], v[74:77]
	v_mfma_f32_16x16x32_bf16 v[70:73], v[160:163], v[228:231], v[70:73]
	v_mfma_f32_16x16x32_bf16 v[66:69], v[168:171], v[228:231], v[66:69]
	v_mfma_f32_16x16x32_bf16 v[110:113], v[164:167], v[192:195], v[110:113]
	v_mfma_f32_16x16x32_bf16 v[106:109], v[172:175], v[192:195], v[106:109]
	v_mfma_f32_16x16x32_bf16 v[94:97], v[164:167], v[216:219], v[94:97]
	v_mfma_f32_16x16x32_bf16 v[90:93], v[172:175], v[216:219], v[90:93]
	v_mfma_f32_16x16x32_bf16 v[78:81], v[164:167], v[224:227], v[78:81]
	v_mfma_f32_16x16x32_bf16 v[74:77], v[172:175], v[224:227], v[74:77]
	v_mfma_f32_16x16x32_bf16 v[70:73], v[164:167], v[232:235], v[70:73]
	v_mfma_f32_16x16x32_bf16 v[66:69], v[172:175], v[232:235], v[66:69]
	s_setprio 0
	s_barrier
	s_add_i32 s63, s63, s18
	v_lshl_add_u64 v[206:207], s[26:27], 0, v[0:1]
	s_mov_b32 m0, s63
	ds_read_b128 v[188:191], v143 offset:16384
	ds_read_b128 v[192:195], v143 offset:17408
	ds_read_b128 v[212:215], v143 offset:18432
	ds_read_b128 v[216:219], v143 offset:19456
	ds_read_b128 v[220:223], v143 offset:20480
	ds_read_b128 v[224:227], v143 offset:21504
	ds_read_b128 v[228:231], v143 offset:22528
	ds_read_b128 v[232:235], v143 offset:23552
	global_load_lds_dwordx4 v[206:207], off
	s_add_i32 m0, s63, 0x2000
	s_add_u32 s70, s26, 0x100000
	v_lshl_add_u64 v[236:237], s[26:27], 0, v[130:131]
	s_addc_u32 s71, s27, 0
	s_add_i32 s63, s73, s18
	global_load_lds_dwordx4 v[236:237], off
	v_lshl_add_u64 v[238:239], s[70:71], 0, v[0:1]
	s_mov_b32 m0, s63
	v_lshl_add_u64 v[240:241], s[28:29], 0, v[132:133]
	global_load_lds_dwordx4 v[238:239], off
	v_lshl_add_u64 v[238:239], s[70:71], 0, v[130:131]
	s_add_i32 m0, s63, 0x2000
	s_nop 0
	global_load_lds_dwordx4 v[238:239], off
	v_lshl_add_u64 v[238:239], s[28:29], 0, v[134:135]
	s_mov_b32 m0, s30
	s_nop 0
	global_load_lds_dwordx4 v[238:239], off
	s_mov_b32 m0, s31
	s_nop 0
	global_load_lds_dwordx4 v[240:241], off
	s_waitcnt vmcnt(8)
	s_waitcnt lgkmcnt(0)
	s_barrier
; #define PG8_STAGE(bufoff, gbase, voff) do { _Pragma("unroll") for (int _i = 0; _i < 2; ++_i) \
;         __builtin_amdgcn_global_load_lds((const unsigned*)((const char*)(gbase) + (voff)[_i]), (PG8_LAS unsigned*)(lds + (bufoff) + ldsw + _i * 8192), 16, 0, 0); } while (0)
; #define PG8_LDA(dst, b, h) do { _Pragma("unroll") for (int m = 0; m < 4; ++m) _Pragma("unroll") for (int k = 0; k < 2; ++k) dst[m][k] = *(const PG8_LAS bf16x8*)(lds + PG8_SA(b, h) + aoff + m * 2048 + k * 1024); } while (0)
; #define PG8_LDB(dst, b, h) do { _Pragma("unroll") for (int n = 0; n < 2; ++n) _Pragma("unroll") for (int k = 0; k < 2; ++k) dst[n][k] = *(const PG8_LAS bf16x8*)(lds + PG8_SB(b, h) + boff + n * 2048 + k * 1024); } while (0)
; #define PG8_MMA(ai, bj, At, Bt) do { __builtin_amdgcn_s_setprio(1); _Pragma("unroll") for (int m = 0; m < 4; ++m) _Pragma("unroll") for (int n = 0; n < 2; ++n) _Pragma("unroll") for (int k = 0; k < 2; ++k) \
;         acc[ai][bj][m][n] = __builtin_amdgcn_mfma_f32_16x16x32_bf16(Bt[n][k], At[m][k], acc[ai][bj][m][n], 0, 0, 0); __builtin_amdgcn_s_setprio(0); } while (0)
; #define PG8_WAIT_V(n) asm volatile("s_waitcnt vmcnt(" #n ")" ::: "memory")
; #define PG8_WAIT_L(n) asm volatile("s_waitcnt lgkmcnt(" #n ")" ::: "memory")
; #define PG8_BAR __builtin_amdgcn_s_barrier()
; #define PG8_SCHED __builtin_amdgcn_sched_barrier(0)
; template <class Epi, class Sched, bool ALIGN_EPI = false, bool SP2 = false>
; __device__ __forceinline__ void gemm_phase(PG8_LAS unsigned char* lds, const Gemm g, const Sched& S, const Epi& E, int wave_s) {
;     ...
;             PG8_WAIT_V(8); PG8_WAIT_L(0); PG8_BAR; PG8_MMA(1, 0, At, B0); PG8_MMA(1, 1, At, B1); PG8_BAR; PG8_SCHED;
;             PG8_LDB(B0, 1, 0); PG8_LDB(B1, 1, 1); PG8_SCHED; PG8_LDA(At, 1, 0); PG8_STAGE(PG8_SA(0, 1), a2 + hstep, voffA);
;             PG8_WAIT_V(8); PG8_WAIT_L(0); PG8_BAR; PG8_MMA(0, 0, At, B0); PG8_MMA(0, 1, At, B1); PG8_BAR; PG8_SCHED;
	s_setprio 1
	s_waitcnt lgkmcnt(0)
	v_mfma_f32_16x16x32_bf16 v[62:65], v[144:147], v[188:191], v[62:65]
	v_mfma_f32_16x16x32_bf16 v[58:61], v[152:155], v[188:191], v[58:61]
	v_mfma_f32_16x16x32_bf16 v[54:57], v[144:147], v[212:215], v[54:57]
	v_mfma_f32_16x16x32_bf16 v[50:53], v[152:155], v[212:215], v[50:53]
	v_mfma_f32_16x16x32_bf16 v[38:41], v[144:147], v[220:223], v[38:41]
	v_mfma_f32_16x16x32_bf16 v[34:37], v[152:155], v[220:223], v[34:37]
	v_mfma_f32_16x16x32_bf16 v[22:25], v[144:147], v[228:231], v[22:25]
	v_mfma_f32_16x16x32_bf16 v[18:21], v[152:155], v[228:231], v[18:21]
	v_mfma_f32_16x16x32_bf16 v[62:65], v[148:151], v[192:195], v[62:65]
	v_mfma_f32_16x16x32_bf16 v[58:61], v[156:159], v[192:195], v[58:61]
	v_mfma_f32_16x16x32_bf16 v[54:57], v[148:151], v[216:219], v[54:57]
	v_mfma_f32_16x16x32_bf16 v[50:53], v[156:159], v[216:219], v[50:53]
	v_mfma_f32_16x16x32_bf16 v[38:41], v[148:151], v[224:227], v[38:41]
	v_mfma_f32_16x16x32_bf16 v[34:37], v[156:159], v[224:227], v[34:37]
	v_mfma_f32_16x16x32_bf16 v[22:25], v[148:151], v[232:235], v[22:25]
	v_mfma_f32_16x16x32_bf16 v[18:21], v[156:159], v[232:235], v[18:21]
	s_setprio 0
	s_setprio 1
	v_mfma_f32_16x16x32_bf16 v[46:49], v[160:163], v[188:191], v[46:49]
	v_mfma_f32_16x16x32_bf16 v[42:45], v[168:171], v[188:191], v[42:45]
	v_mfma_f32_16x16x32_bf16 v[30:33], v[160:163], v[212:215], v[30:33]
	v_mfma_f32_16x16x32_bf16 v[26:29], v[168:171], v[212:215], v[26:29]
	v_mfma_f32_16x16x32_bf16 v[14:17], v[160:163], v[220:223], v[14:17]
	v_mfma_f32_16x16x32_bf16 v[10:13], v[168:171], v[220:223], v[10:13]
	v_mfma_f32_16x16x32_bf16 v[6:9], v[160:163], v[228:231], v[6:9]
	v_mfma_f32_16x16x32_bf16 v[2:5], v[168:171], v[228:231], v[2:5]
	v_mfma_f32_16x16x32_bf16 v[46:49], v[164:167], v[192:195], v[46:49]
	v_mfma_f32_16x16x32_bf16 v[42:45], v[172:175], v[192:195], v[42:45]
	v_mfma_f32_16x16x32_bf16 v[30:33], v[164:167], v[216:219], v[30:33]
	v_mfma_f32_16x16x32_bf16 v[26:29], v[172:175], v[216:219], v[26:29]
	v_mfma_f32_16x16x32_bf16 v[14:17], v[164:167], v[224:227], v[14:17]
	v_mfma_f32_16x16x32_bf16 v[10:13], v[172:175], v[224:227], v[10:13]
	v_mfma_f32_16x16x32_bf16 v[6:9], v[164:167], v[232:235], v[6:9]
	v_mfma_f32_16x16x32_bf16 v[2:5], v[172:175], v[232:235], v[2:5]
	s_setprio 0
	s_barrier
	s_add_i32 s63, 0, 0x18000
	s_add_i32 s70, 0, 0x1c000
	v_add_u32_e32 v156, s63, v141
	v_add_u32_e32 v172, s70, v141
	ds_read_b128 v[144:147], v156
	ds_read_b128 v[148:151], v156 offset:1024
	ds_read_b128 v[152:155], v156 offset:2048
	ds_read_b128 v[156:159], v156 offset:3072
	ds_read_b128 v[160:163], v172
	ds_read_b128 v[164:167], v172 offset:1024
	ds_read_b128 v[168:171], v172 offset:2048
	ds_read_b128 v[172:175], v172 offset:3072
	s_add_u32 s28, s28, 0x100000
	s_addc_u32 s29, s29, 0
	s_mov_b32 m0, s34
	v_lshl_add_u64 v[242:243], s[28:29], 0, v[134:135]
	ds_read_b128 v[188:191], v143 offset:32768
	ds_read_b128 v[192:195], v143 offset:33792
	ds_read_b128 v[212:215], v143 offset:34816
	ds_read_b128 v[216:219], v143 offset:35840
	ds_read_b128 v[220:223], v143 offset:36864
	ds_read_b128 v[224:227], v143 offset:37888
	ds_read_b128 v[228:231], v143 offset:38912
	ds_read_b128 v[232:235], v143 offset:39936
	global_load_lds_dwordx4 v[242:243], off
	v_lshl_add_u64 v[242:243], s[28:29], 0, v[132:133]
	s_mov_b32 m0, s35
	s_nop 0
	global_load_lds_dwordx4 v[242:243], off
	s_waitcnt vmcnt(8)
	s_waitcnt lgkmcnt(0)
	s_barrier
	s_setprio 1
	s_waitcnt lgkmcnt(0)
	v_mfma_f32_16x16x32_bf16 v[126:129], v[144:147], v[188:191], v[126:129]
	v_mfma_f32_16x16x32_bf16 v[122:125], v[152:155], v[188:191], v[122:125]
	v_mfma_f32_16x16x32_bf16 v[118:121], v[144:147], v[212:215], v[118:121]
	v_mfma_f32_16x16x32_bf16 v[114:117], v[152:155], v[212:215], v[114:117]
	v_mfma_f32_16x16x32_bf16 v[102:105], v[144:147], v[220:223], v[102:105]
	v_mfma_f32_16x16x32_bf16 v[98:101], v[152:155], v[220:223], v[98:101]
	v_mfma_f32_16x16x32_bf16 v[86:89], v[144:147], v[228:231], v[86:89]
	v_mfma_f32_16x16x32_bf16 v[82:85], v[152:155], v[228:231], v[82:85]
	v_mfma_f32_16x16x32_bf16 v[126:129], v[148:151], v[192:195], v[126:129]
	v_mfma_f32_16x16x32_bf16 v[122:125], v[156:159], v[192:195], v[122:125]
	v_mfma_f32_16x16x32_bf16 v[118:121], v[148:151], v[216:219], v[118:121]
	v_mfma_f32_16x16x32_bf16 v[114:117], v[156:159], v[216:219], v[114:117]
	v_mfma_f32_16x16x32_bf16 v[102:105], v[148:151], v[224:227], v[102:105]
	v_mfma_f32_16x16x32_bf16 v[98:101], v[156:159], v[224:227], v[98:101]
	v_mfma_f32_16x16x32_bf16 v[86:89], v[148:151], v[232:235], v[86:89]
	v_mfma_f32_16x16x32_bf16 v[82:85], v[156:159], v[232:235], v[82:85]
	s_setprio 0
	s_setprio 1
	v_mfma_f32_16x16x32_bf16 v[110:113], v[160:163], v[188:191], v[110:113]
	v_mfma_f32_16x16x32_bf16 v[106:109], v[168:171], v[188:191], v[106:109]
	v_mfma_f32_16x16x32_bf16 v[94:97], v[160:163], v[212:215], v[94:97]
	v_mfma_f32_16x16x32_bf16 v[90:93], v[168:171], v[212:215], v[90:93]
	v_mfma_f32_16x16x32_bf16 v[78:81], v[160:163], v[220:223], v[78:81]
	v_mfma_f32_16x16x32_bf16 v[74:77], v[168:171], v[220:223], v[74:77]
	v_mfma_f32_16x16x32_bf16 v[70:73], v[160:163], v[228:231], v[70:73]
	v_mfma_f32_16x16x32_bf16 v[66:69], v[168:171], v[228:231], v[66:69]
	v_mfma_f32_16x16x32_bf16 v[110:113], v[164:167], v[192:195], v[110:113]
	v_mfma_f32_16x16x32_bf16 v[106:109], v[172:175], v[192:195], v[106:109]
	v_mfma_f32_16x16x32_bf16 v[94:97], v[164:167], v[216:219], v[94:97]
	v_mfma_f32_16x16x32_bf16 v[90:93], v[172:175], v[216:219], v[90:93]
	v_mfma_f32_16x16x32_bf16 v[78:81], v[164:167], v[224:227], v[78:81]
	v_mfma_f32_16x16x32_bf16 v[74:77], v[172:175], v[224:227], v[74:77]
	v_mfma_f32_16x16x32_bf16 v[70:73], v[164:167], v[232:235], v[70:73]
	v_mfma_f32_16x16x32_bf16 v[66:69], v[172:175], v[232:235], v[66:69]
	s_setprio 0
	s_barrier
; #define PG8_STAGE(bufoff, gbase, voff) do { _Pragma("unroll") for (int _i = 0; _i < 2; ++_i) \
;         __builtin_amdgcn_global_load_lds((const unsigned*)((const char*)(gbase) + (voff)[_i]), (PG8_LAS unsigned*)(lds + (bufoff) + ldsw + _i * 8192), 16, 0, 0); } while (0)
; #define PG8_LDA(dst, b, h) do { _Pragma("unroll") for (int m = 0; m < 4; ++m) _Pragma("unroll") for (int k = 0; k < 2; ++k) dst[m][k] = *(const PG8_LAS bf16x8*)(lds + PG8_SA(b, h) + aoff + m * 2048 + k * 1024); } while (0)
; #define PG8_MMA(ai, bj, At, Bt) do { __builtin_amdgcn_s_setprio(1); _Pragma("unroll") for (int m = 0; m < 4; ++m) _Pragma("unroll") for (int n = 0; n < 2; ++n) _Pragma("unroll") for (int k = 0; k < 2; ++k) \
;         acc[ai][bj][m][n] = __builtin_amdgcn_mfma_f32_16x16x32_bf16(Bt[n][k], At[m][k], acc[ai][bj][m][n], 0, 0, 0); __builtin_amdgcn_s_setprio(0); } while (0)
; #define PG8_WAIT_V(n) asm volatile("s_waitcnt vmcnt(" #n ")" ::: "memory")
; #define PG8_WAIT_L(n) asm volatile("s_waitcnt lgkmcnt(" #n ")" ::: "memory")
; #define PG8_BAR __builtin_amdgcn_s_barrier()
; #define PG8_SCHED __builtin_amdgcn_sched_barrier(0)
; template <class Epi, class Sched, bool ALIGN_EPI = false, bool SP2 = false>
; __device__ __forceinline__ void gemm_phase(PG8_LAS unsigned char* lds, const Gemm g, const Sched& S, const Epi& E, int wave_s) {
;     ...
;         for (int t = 0; t < nt; t += 2) {
;     ...
;             PG8_LDA(At, 1, 1); PG8_STAGE(PG8_SB(1, 0), b3, voffB); PG8_STAGE(PG8_SB(1, 1), b3 + hstep, voffB); PG8_STAGE(PG8_SA(1, 0), a3, voffA);
;             PG8_WAIT_V(8); PG8_WAIT_L(0); PG8_BAR; PG8_MMA(1, 0, At, B0); PG8_MMA(1, 1, At, B1); PG8_BAR; PG8_SCHED;
	s_add_i32 s28, s63, s18
	v_lshl_add_u64 v[206:207], v[206:207], 0, s[68:69]
	s_mov_b32 m0, s28
	ds_read_b128 v[188:191], v143 offset:49152
	ds_read_b128 v[192:195], v143 offset:50176
	ds_read_b128 v[212:215], v143 offset:51200
	ds_read_b128 v[216:219], v143 offset:52224
	ds_read_b128 v[220:223], v143 offset:53248
	ds_read_b128 v[224:227], v143 offset:54272
	ds_read_b128 v[228:231], v143 offset:55296
	ds_read_b128 v[232:235], v143 offset:56320
	global_load_lds_dwordx4 v[206:207], off
	s_add_i32 m0, s28, 0x2000
	s_add_u32 s26, s26, 0x100080
	v_lshl_add_u64 v[206:207], v[236:237], 0, s[68:69]
	s_addc_u32 s27, s27, 0
	s_add_i32 s28, s70, s18
	global_load_lds_dwordx4 v[206:207], off
	v_lshl_add_u64 v[206:207], s[26:27], 0, v[0:1]
	s_mov_b32 m0, s28
	s_nop 0
	global_load_lds_dwordx4 v[206:207], off
	v_lshl_add_u64 v[206:207], s[26:27], 0, v[130:131]
	s_add_i32 m0, s28, 0x2000
	s_nop 0
	global_load_lds_dwordx4 v[206:207], off
	v_lshl_add_u64 v[206:207], v[238:239], 0, s[68:69]
	s_mov_b32 m0, s36
	s_nop 0
	global_load_lds_dwordx4 v[206:207], off
	v_lshl_add_u64 v[206:207], v[240:241], 0, s[68:69]
	s_mov_b32 m0, s37
	s_nop 0
	global_load_lds_dwordx4 v[206:207], off
	s_waitcnt vmcnt(8)
	s_waitcnt lgkmcnt(0)
	s_barrier
	s_setprio 1
	s_waitcnt lgkmcnt(0)
	v_mfma_f32_16x16x32_bf16 v[62:65], v[144:147], v[188:191], v[62:65]
	v_mfma_f32_16x16x32_bf16 v[58:61], v[152:155], v[188:191], v[58:61]
	v_mfma_f32_16x16x32_bf16 v[54:57], v[144:147], v[212:215], v[54:57]
	v_mfma_f32_16x16x32_bf16 v[50:53], v[152:155], v[212:215], v[50:53]
	v_mfma_f32_16x16x32_bf16 v[38:41], v[144:147], v[220:223], v[38:41]
	v_mfma_f32_16x16x32_bf16 v[34:37], v[152:155], v[220:223], v[34:37]
	v_mfma_f32_16x16x32_bf16 v[22:25], v[144:147], v[228:231], v[22:25]
	v_mfma_f32_16x16x32_bf16 v[18:21], v[152:155], v[228:231], v[18:21]
	v_mfma_f32_16x16x32_bf16 v[62:65], v[148:151], v[192:195], v[62:65]
	v_mfma_f32_16x16x32_bf16 v[58:61], v[156:159], v[192:195], v[58:61]
	v_mfma_f32_16x16x32_bf16 v[54:57], v[148:151], v[216:219], v[54:57]
	v_mfma_f32_16x16x32_bf16 v[50:53], v[156:159], v[216:219], v[50:53]
	v_mfma_f32_16x16x32_bf16 v[38:41], v[148:151], v[224:227], v[38:41]
	v_mfma_f32_16x16x32_bf16 v[34:37], v[156:159], v[224:227], v[34:37]
	v_mfma_f32_16x16x32_bf16 v[22:25], v[148:151], v[232:235], v[22:25]
	v_mfma_f32_16x16x32_bf16 v[18:21], v[156:159], v[232:235], v[18:21]
	s_setprio 0
	s_setprio 1
	v_mfma_f32_16x16x32_bf16 v[46:49], v[160:163], v[188:191], v[46:49]
	v_mfma_f32_16x16x32_bf16 v[42:45], v[168:171], v[188:191], v[42:45]
	v_mfma_f32_16x16x32_bf16 v[30:33], v[160:163], v[212:215], v[30:33]
	v_mfma_f32_16x16x32_bf16 v[26:29], v[168:171], v[212:215], v[26:29]
	v_mfma_f32_16x16x32_bf16 v[14:17], v[160:163], v[220:223], v[14:17]
	v_mfma_f32_16x16x32_bf16 v[10:13], v[168:171], v[220:223], v[10:13]
	v_mfma_f32_16x16x32_bf16 v[6:9], v[160:163], v[228:231], v[6:9]
	v_mfma_f32_16x16x32_bf16 v[2:5], v[168:171], v[228:231], v[2:5]
	v_mfma_f32_16x16x32_bf16 v[46:49], v[164:167], v[192:195], v[46:49]
	v_mfma_f32_16x16x32_bf16 v[42:45], v[172:175], v[192:195], v[42:45]
	v_mfma_f32_16x16x32_bf16 v[30:33], v[164:167], v[216:219], v[30:33]
	v_mfma_f32_16x16x32_bf16 v[26:29], v[172:175], v[216:219], v[26:29]
	v_mfma_f32_16x16x32_bf16 v[14:17], v[164:167], v[224:227], v[14:17]
	v_mfma_f32_16x16x32_bf16 v[10:13], v[172:175], v[224:227], v[10:13]
	v_mfma_f32_16x16x32_bf16 v[6:9], v[164:167], v[232:235], v[6:9]
	v_mfma_f32_16x16x32_bf16 v[2:5], v[172:175], v[232:235], v[2:5]
	s_add_i32 s57, s57, 2
	s_add_u32 s24, s24, 0x100
	s_addc_u32 s25, s25, 0
	s_add_u32 s45, s45, 0x100
	s_addc_u32 s51, s51, 0
	s_setprio 0
	s_barrier
	s_cmp_gt_u32 s57, 61
	s_cbranch_scc0 .LBB0_986
	s_and_b64 vcc, exec, s[58:59]
	s_cbranch_vccz .LBB0_989
	s_barrier
